# speedup vs baseline: 1.0116x; 1.0116x over previous
; #define PG8_STAGE(bufoff, gbase, voff) do { _Pragma("unroll") for (int _i = 0; _i < 2; ++_i) \
;         __builtin_amdgcn_global_load_lds((const unsigned*)((const char*)(gbase) + (voff)[_i]), (LAS unsigned*)(lds + (bufoff) + ldsw + _i * 8192), 16, 0, 0); } while (0)
; #define PG8_LDA(dst, b, h) do { _Pragma("unroll") for (int m = 0; m < 4; ++m) _Pragma("unroll") for (int k = 0; k < 2; ++k) dst[m][k] = *(const LAS bf16x8*)(lds + PG8_SA(b, h) + aoff + m * 2048 + k * 1024); } while (0)
; #define PG8_LDB(dst, b, h) do { _Pragma("unroll") for (int n = 0; n < 2; ++n) _Pragma("unroll") for (int k = 0; k < 2; ++k) dst[n][k] = *(const LAS bf16x8*)(lds + PG8_SB(b, h) + boff + n * 2048 + k * 1024); } while (0)
; #define PG8_MMA(ai, bj, At, Bt) do { __builtin_amdgcn_s_setprio(1); _Pragma("unroll") for (int m = 0; m < 4; ++m) _Pragma("unroll") for (int n = 0; n < 2; ++n) _Pragma("unroll") for (int k = 0; k < 2; ++k) \
;         acc[ai][bj][m][n] = __builtin_amdgcn_mfma_f32_16x16x32_bf16(Bt[n][k], At[m][k], acc[ai][bj][m][n], 0, 0, 0); __builtin_amdgcn_s_setprio(0); } while (0)
; #define PG8_WAIT_V(n) asm volatile("s_waitcnt vmcnt(" #n ")" ::: "memory")
; #define PG8_WAIT_L(n) asm volatile("s_waitcnt lgkmcnt(" #n ")" ::: "memory")
; #define PG8_BAR __builtin_amdgcn_s_barrier()
; template <class Epi, class Sched, bool HN = false>
; __device__ __forceinline__ void gemm_phase(LAS unsigned char* lds, const Gemm g, const Sched& S, const Epi& E) {
;     ...
;             const char* a1 = cA + (size_t)(t + 1) * kstep;
;             const char* a2 = last ? nA : cA + (size_t)(t + 2) * kstep; const char* b2 = last ? nB : cB + (size_t)(t + 2) * kstep;
;             const char* a3 = a2 + kstep; const char* b3 = b2 + kstep;
;             if constexpr (Epi::MID) { if (t == (nt >> 1)) E.mid(acc, wid, fr, lds); }
;             if constexpr (!HN) {
;             PG8_LDB(B0, 0, 0); PG8_LDB(B1, 0, 1); PG8_SCHED; PG8_LDA(At, 0, 0); PG8_STAGE(PG8_SA(1, 1), a1 + hstep, voffA);
;             PG8_WAIT_V(8); PG8_WAIT_L(0); PG8_BAR; PG8_MMA(0, 0, At, B0); PG8_MMA(0, 1, At, B1); PG8_BAR; PG8_SCHED;
;             PG8_LDA(At, 0, 1); PG8_STAGE(PG8_SB(0, 0), b2, voffB); PG8_STAGE(PG8_SB(0, 1), b2 + hstep, voffB); PG8_STAGE(PG8_SA(0, 0), a2, voffA);
;             PG8_WAIT_V(8); PG8_WAIT_L(0); PG8_BAR; PG8_MMA(1, 0, At, B0); PG8_MMA(1, 1, At, B1); PG8_BAR; PG8_SCHED;
.LBB0_209:
	s_add_u32 s56, s30, 0xfff80080
	s_addc_u32 s57, s31, -1
	s_add_i32 s79, 0, 0x10000
	s_cmp_eq_u32 s78, 28
	s_cselect_b32 s59, s1, s57
	s_cselect_b32 s58, s51, s56
	v_add_u32_e32 v24, s79, v177
	s_cselect_b32 s57, s49, s77
	s_cselect_b32 s56, s74, s76
	s_add_i32 s83, 0, 0x14000
	ds_read_b128 v[130:133], v24
	ds_read_b128 v[134:137], v24 offset:1024
	ds_read_b128 v[138:141], v24 offset:2048
	ds_read_b128 v[166:169], v24 offset:3072
	v_add_u32_e32 v24, s83, v177
	ds_read_b128 v[170:173], v24
	ds_read_b128 v[182:185], v24 offset:1024
	ds_read_b128 v[186:189], v24 offset:2048
	ds_read_b128 v[190:193], v24 offset:3072
	v_lshl_add_u64 v[174:175], s[30:31], 0, v[162:163]
	s_add_i32 m0, s41, 0xc000
	ds_read_b128 v[194:197], v179
	ds_read_b128 v[208:211], v179 offset:1024
	ds_read_b128 v[212:215], v179 offset:2048
	ds_read_b128 v[226:229], v179 offset:3072
	ds_read_b128 v[230:233], v179 offset:4096
	ds_read_b128 v[234:237], v179 offset:5120
	ds_read_b128 v[238:241], v179 offset:6144
	ds_read_b128 v[242:245], v179 offset:7168
	global_load_lds_dwordx4 v[174:175], off
	v_lshl_add_u64 v[174:175], s[30:31], 0, v[164:165]
	s_add_i32 m0, s41, 0xe000
	s_nop 0
	global_load_lds_dwordx4 v[174:175], off
	s_waitcnt vmcnt(8)
	s_waitcnt lgkmcnt(0)
	s_barrier
	s_setprio 1
	s_waitcnt lgkmcnt(0)
	v_mfma_f32_16x16x32_bf16 v[126:129], v[130:133], v[194:197], v[126:129]
	v_mfma_f32_16x16x32_bf16 v[122:125], v[138:141], v[194:197], v[122:125]
	v_mfma_f32_16x16x32_bf16 v[110:113], v[130:133], v[212:215], v[110:113]
	v_mfma_f32_16x16x32_bf16 v[106:109], v[138:141], v[212:215], v[106:109]
	v_mfma_f32_16x16x32_bf16 v[94:97], v[130:133], v[230:233], v[94:97]
	v_mfma_f32_16x16x32_bf16 v[90:93], v[138:141], v[230:233], v[90:93]
	v_mfma_f32_16x16x32_bf16 v[78:81], v[130:133], v[238:241], v[78:81]
	v_mfma_f32_16x16x32_bf16 v[74:77], v[138:141], v[238:241], v[74:77]
	v_mfma_f32_16x16x32_bf16 v[126:129], v[134:137], v[208:211], v[126:129]
	v_mfma_f32_16x16x32_bf16 v[122:125], v[166:169], v[208:211], v[122:125]
	v_mfma_f32_16x16x32_bf16 v[110:113], v[134:137], v[226:229], v[110:113]
	v_mfma_f32_16x16x32_bf16 v[106:109], v[166:169], v[226:229], v[106:109]
	v_mfma_f32_16x16x32_bf16 v[94:97], v[134:137], v[234:237], v[94:97]
	v_mfma_f32_16x16x32_bf16 v[90:93], v[166:169], v[234:237], v[90:93]
	v_mfma_f32_16x16x32_bf16 v[78:81], v[134:137], v[242:245], v[78:81]
	v_mfma_f32_16x16x32_bf16 v[74:77], v[166:169], v[242:245], v[74:77]
	s_setprio 0
	s_setprio 1
	v_mfma_f32_16x16x32_bf16 v[118:121], v[170:173], v[194:197], v[118:121]
	v_mfma_f32_16x16x32_bf16 v[114:117], v[186:189], v[194:197], v[114:117]
	v_mfma_f32_16x16x32_bf16 v[102:105], v[170:173], v[212:215], v[102:105]
	v_mfma_f32_16x16x32_bf16 v[98:101], v[186:189], v[212:215], v[98:101]
	v_mfma_f32_16x16x32_bf16 v[86:89], v[170:173], v[230:233], v[86:89]
	v_mfma_f32_16x16x32_bf16 v[82:85], v[186:189], v[230:233], v[82:85]
	v_mfma_f32_16x16x32_bf16 v[70:73], v[170:173], v[238:241], v[70:73]
	v_mfma_f32_16x16x32_bf16 v[66:69], v[186:189], v[238:241], v[66:69]
	v_mfma_f32_16x16x32_bf16 v[118:121], v[182:185], v[208:211], v[118:121]
	v_mfma_f32_16x16x32_bf16 v[114:117], v[190:193], v[208:211], v[114:117]
	v_mfma_f32_16x16x32_bf16 v[102:105], v[182:185], v[226:229], v[102:105]
	v_mfma_f32_16x16x32_bf16 v[98:101], v[190:193], v[226:229], v[98:101]
	v_mfma_f32_16x16x32_bf16 v[86:89], v[182:185], v[234:237], v[86:89]
	v_mfma_f32_16x16x32_bf16 v[82:85], v[190:193], v[234:237], v[82:85]
	v_mfma_f32_16x16x32_bf16 v[70:73], v[182:185], v[242:245], v[70:73]
	v_mfma_f32_16x16x32_bf16 v[66:69], v[190:193], v[242:245], v[66:69]
	s_setprio 0
	s_barrier
	s_add_i32 s79, s79, s63
	v_lshl_add_u64 v[174:175], s[56:57], 0, v[144:145]
	s_mov_b32 m0, s79
	ds_read_b128 v[194:197], v179 offset:16384
	ds_read_b128 v[208:211], v179 offset:17408
	ds_read_b128 v[212:215], v179 offset:18432
	ds_read_b128 v[226:229], v179 offset:19456
	ds_read_b128 v[230:233], v179 offset:20480
	ds_read_b128 v[234:237], v179 offset:21504
	ds_read_b128 v[238:241], v179 offset:22528
	ds_read_b128 v[242:245], v179 offset:23552
	global_load_lds_dwordx4 v[174:175], off
	s_add_i32 m0, s79, 0x2000
	s_add_u32 s84, s56, 0x80000
	v_lshl_add_u64 v[246:247], s[56:57], 0, v[148:149]
	s_addc_u32 s85, s57, 0
	s_add_i32 s79, s83, s63
	global_load_lds_dwordx4 v[246:247], off
	v_lshl_add_u64 v[248:249], s[84:85], 0, v[144:145]
	s_mov_b32 m0, s79
	v_lshl_add_u64 v[250:251], s[58:59], 0, v[146:147]
	global_load_lds_dwordx4 v[248:249], off
	v_lshl_add_u64 v[248:249], s[84:85], 0, v[148:149]
	s_add_i32 m0, s79, 0x2000
	s_nop 0
	global_load_lds_dwordx4 v[248:249], off
	v_lshl_add_u64 v[248:249], s[58:59], 0, v[142:143]
	s_mov_b32 m0, s41
	s_nop 0
	global_load_lds_dwordx4 v[248:249], off
	s_mov_b32 m0, s64
	s_nop 0
	global_load_lds_dwordx4 v[250:251], off
	s_waitcnt vmcnt(8)
	s_waitcnt lgkmcnt(0)
	s_barrier
; #define PG8_STAGE(bufoff, gbase, voff) do { _Pragma("unroll") for (int _i = 0; _i < 2; ++_i) \
;         __builtin_amdgcn_global_load_lds((const unsigned*)((const char*)(gbase) + (voff)[_i]), (LAS unsigned*)(lds + (bufoff) + ldsw + _i * 8192), 16, 0, 0); } while (0)
; #define PG8_LDA(dst, b, h) do { _Pragma("unroll") for (int m = 0; m < 4; ++m) _Pragma("unroll") for (int k = 0; k < 2; ++k) dst[m][k] = *(const LAS bf16x8*)(lds + PG8_SA(b, h) + aoff + m * 2048 + k * 1024); } while (0)
; #define PG8_LDB(dst, b, h) do { _Pragma("unroll") for (int n = 0; n < 2; ++n) _Pragma("unroll") for (int k = 0; k < 2; ++k) dst[n][k] = *(const LAS bf16x8*)(lds + PG8_SB(b, h) + boff + n * 2048 + k * 1024); } while (0)
; #define PG8_MMA(ai, bj, At, Bt) do { __builtin_amdgcn_s_setprio(1); _Pragma("unroll") for (int m = 0; m < 4; ++m) _Pragma("unroll") for (int n = 0; n < 2; ++n) _Pragma("unroll") for (int k = 0; k < 2; ++k) \
;         acc[ai][bj][m][n] = __builtin_amdgcn_mfma_f32_16x16x32_bf16(Bt[n][k], At[m][k], acc[ai][bj][m][n], 0, 0, 0); __builtin_amdgcn_s_setprio(0); } while (0)
; #define PG8_WAIT_V(n) asm volatile("s_waitcnt vmcnt(" #n ")" ::: "memory")
; #define PG8_WAIT_L(n) asm volatile("s_waitcnt lgkmcnt(" #n ")" ::: "memory")
; #define PG8_BAR __builtin_amdgcn_s_barrier()
; #define PG8_SCHED __builtin_amdgcn_sched_barrier(0)
; template <class Epi, class Sched, bool HN = false>
; __device__ __forceinline__ void gemm_phase(LAS unsigned char* lds, const Gemm g, const Sched& S, const Epi& E) {
;     ...
;             PG8_WAIT_V(8); PG8_WAIT_L(0); PG8_BAR; PG8_MMA(1, 0, At, B0); PG8_MMA(1, 1, At, B1); PG8_BAR; PG8_SCHED;
;             PG8_LDB(B0, 1, 0); PG8_LDB(B1, 1, 1); PG8_SCHED; PG8_LDA(At, 1, 0); PG8_STAGE(PG8_SA(0, 1), a2 + hstep, voffA);
;             PG8_WAIT_V(8); PG8_WAIT_L(0); PG8_BAR; PG8_MMA(0, 0, At, B0); PG8_MMA(0, 1, At, B1); PG8_BAR; PG8_SCHED;
	s_setprio 1
	s_waitcnt lgkmcnt(0)
	v_mfma_f32_16x16x32_bf16 v[62:65], v[130:133], v[194:197], v[62:65]
	v_mfma_f32_16x16x32_bf16 v[58:61], v[138:141], v[194:197], v[58:61]
	v_mfma_f32_16x16x32_bf16 v[46:49], v[130:133], v[212:215], v[46:49]
	v_mfma_f32_16x16x32_bf16 v[42:45], v[138:141], v[212:215], v[42:45]
	v_mfma_f32_16x16x32_bf16 v[30:33], v[130:133], v[230:233], v[30:33]
	v_mfma_f32_16x16x32_bf16 v[26:29], v[138:141], v[230:233], v[26:29]
	v_mfma_f32_16x16x32_bf16 v[12:15], v[130:133], v[238:241], v[12:15]
	v_mfma_f32_16x16x32_bf16 v[8:11], v[138:141], v[238:241], v[8:11]
	v_mfma_f32_16x16x32_bf16 v[62:65], v[134:137], v[208:211], v[62:65]
	v_mfma_f32_16x16x32_bf16 v[58:61], v[166:169], v[208:211], v[58:61]
	v_mfma_f32_16x16x32_bf16 v[46:49], v[134:137], v[226:229], v[46:49]
	v_mfma_f32_16x16x32_bf16 v[42:45], v[166:169], v[226:229], v[42:45]
	v_mfma_f32_16x16x32_bf16 v[30:33], v[134:137], v[234:237], v[30:33]
	v_mfma_f32_16x16x32_bf16 v[26:29], v[166:169], v[234:237], v[26:29]
	v_mfma_f32_16x16x32_bf16 v[12:15], v[134:137], v[242:245], v[12:15]
	v_mfma_f32_16x16x32_bf16 v[8:11], v[166:169], v[242:245], v[8:11]
	s_setprio 0
	s_setprio 1
	v_mfma_f32_16x16x32_bf16 v[54:57], v[170:173], v[194:197], v[54:57]
	v_mfma_f32_16x16x32_bf16 v[50:53], v[186:189], v[194:197], v[50:53]
	v_mfma_f32_16x16x32_bf16 v[38:41], v[170:173], v[212:215], v[38:41]
	v_mfma_f32_16x16x32_bf16 v[34:37], v[186:189], v[212:215], v[34:37]
	v_mfma_f32_16x16x32_bf16 v[20:23], v[170:173], v[230:233], v[20:23]
	v_mfma_f32_16x16x32_bf16 v[16:19], v[186:189], v[230:233], v[16:19]
	v_mfma_f32_16x16x32_bf16 v[4:7], v[170:173], v[238:241], v[4:7]
	v_mfma_f32_16x16x32_bf16 v[0:3], v[186:189], v[238:241], v[0:3]
	v_mfma_f32_16x16x32_bf16 v[54:57], v[182:185], v[208:211], v[54:57]
	v_mfma_f32_16x16x32_bf16 v[50:53], v[190:193], v[208:211], v[50:53]
	v_mfma_f32_16x16x32_bf16 v[38:41], v[182:185], v[226:229], v[38:41]
	v_mfma_f32_16x16x32_bf16 v[34:37], v[190:193], v[226:229], v[34:37]
	v_mfma_f32_16x16x32_bf16 v[20:23], v[182:185], v[234:237], v[20:23]
	v_mfma_f32_16x16x32_bf16 v[16:19], v[190:193], v[234:237], v[16:19]
	v_mfma_f32_16x16x32_bf16 v[4:7], v[182:185], v[242:245], v[4:7]
	v_mfma_f32_16x16x32_bf16 v[0:3], v[190:193], v[242:245], v[0:3]
	s_setprio 0
	s_barrier
	s_add_i32 s79, 0, 0x18000
	v_add_u32_e32 v24, s79, v177
	s_add_i32 s83, 0, 0x1c000
	ds_read_b128 v[130:133], v24
	ds_read_b128 v[134:137], v24 offset:1024
	ds_read_b128 v[138:141], v24 offset:2048
	ds_read_b128 v[166:169], v24 offset:3072
	v_add_u32_e32 v24, s83, v177
	ds_read_b128 v[170:173], v24
	ds_read_b128 v[182:185], v24 offset:1024
	ds_read_b128 v[186:189], v24 offset:2048
	ds_read_b128 v[190:193], v24 offset:3072
	s_add_u32 s58, s58, 0x80000
	s_addc_u32 s59, s59, 0
	s_mov_b32 m0, s65
	v_lshl_add_u64 v[216:217], s[58:59], 0, v[142:143]
	ds_read_b128 v[194:197], v179 offset:32768
	ds_read_b128 v[208:211], v179 offset:33792
	ds_read_b128 v[212:215], v179 offset:34816
	ds_read_b128 v[226:229], v179 offset:35840
	ds_read_b128 v[230:233], v179 offset:36864
	ds_read_b128 v[234:237], v179 offset:37888
	ds_read_b128 v[238:241], v179 offset:38912
	ds_read_b128 v[242:245], v179 offset:39936
	global_load_lds_dwordx4 v[216:217], off
	v_lshl_add_u64 v[216:217], s[58:59], 0, v[146:147]
	s_mov_b32 m0, s66
	s_nop 0
	global_load_lds_dwordx4 v[216:217], off
	s_waitcnt vmcnt(8)
	s_waitcnt lgkmcnt(0)
	s_barrier
	s_setprio 1
	s_waitcnt lgkmcnt(0)
	v_mfma_f32_16x16x32_bf16 v[126:129], v[130:133], v[194:197], v[126:129]
	v_mfma_f32_16x16x32_bf16 v[122:125], v[138:141], v[194:197], v[122:125]
	v_mfma_f32_16x16x32_bf16 v[110:113], v[130:133], v[212:215], v[110:113]
	v_mfma_f32_16x16x32_bf16 v[106:109], v[138:141], v[212:215], v[106:109]
	v_mfma_f32_16x16x32_bf16 v[94:97], v[130:133], v[230:233], v[94:97]
	v_mfma_f32_16x16x32_bf16 v[90:93], v[138:141], v[230:233], v[90:93]
	v_mfma_f32_16x16x32_bf16 v[78:81], v[130:133], v[238:241], v[78:81]
	v_mfma_f32_16x16x32_bf16 v[74:77], v[138:141], v[238:241], v[74:77]
	v_mfma_f32_16x16x32_bf16 v[126:129], v[134:137], v[208:211], v[126:129]
	v_mfma_f32_16x16x32_bf16 v[122:125], v[166:169], v[208:211], v[122:125]
	v_mfma_f32_16x16x32_bf16 v[110:113], v[134:137], v[226:229], v[110:113]
	v_mfma_f32_16x16x32_bf16 v[106:109], v[166:169], v[226:229], v[106:109]
	v_mfma_f32_16x16x32_bf16 v[94:97], v[134:137], v[234:237], v[94:97]
	v_mfma_f32_16x16x32_bf16 v[90:93], v[166:169], v[234:237], v[90:93]
	v_mfma_f32_16x16x32_bf16 v[78:81], v[134:137], v[242:245], v[78:81]
	v_mfma_f32_16x16x32_bf16 v[74:77], v[166:169], v[242:245], v[74:77]
	s_setprio 0
	s_setprio 1
	v_mfma_f32_16x16x32_bf16 v[118:121], v[170:173], v[194:197], v[118:121]
	v_mfma_f32_16x16x32_bf16 v[114:117], v[186:189], v[194:197], v[114:117]
	v_mfma_f32_16x16x32_bf16 v[102:105], v[170:173], v[212:215], v[102:105]
	v_mfma_f32_16x16x32_bf16 v[98:101], v[186:189], v[212:215], v[98:101]
	v_mfma_f32_16x16x32_bf16 v[86:89], v[170:173], v[230:233], v[86:89]
	v_mfma_f32_16x16x32_bf16 v[82:85], v[186:189], v[230:233], v[82:85]
	v_mfma_f32_16x16x32_bf16 v[70:73], v[170:173], v[238:241], v[70:73]
	v_mfma_f32_16x16x32_bf16 v[66:69], v[186:189], v[238:241], v[66:69]
	v_mfma_f32_16x16x32_bf16 v[118:121], v[182:185], v[208:211], v[118:121]
	v_mfma_f32_16x16x32_bf16 v[114:117], v[190:193], v[208:211], v[114:117]
	v_mfma_f32_16x16x32_bf16 v[102:105], v[182:185], v[226:229], v[102:105]
	v_mfma_f32_16x16x32_bf16 v[98:101], v[190:193], v[226:229], v[98:101]
	v_mfma_f32_16x16x32_bf16 v[86:89], v[182:185], v[234:237], v[86:89]
	v_mfma_f32_16x16x32_bf16 v[82:85], v[190:193], v[234:237], v[82:85]
	v_mfma_f32_16x16x32_bf16 v[70:73], v[182:185], v[242:245], v[70:73]
	v_mfma_f32_16x16x32_bf16 v[66:69], v[190:193], v[242:245], v[66:69]
	s_setprio 0
	s_barrier
; #define PG8_STAGE(bufoff, gbase, voff) do { _Pragma("unroll") for (int _i = 0; _i < 2; ++_i) \
;         __builtin_amdgcn_global_load_lds((const unsigned*)((const char*)(gbase) + (voff)[_i]), (LAS unsigned*)(lds + (bufoff) + ldsw + _i * 8192), 16, 0, 0); } while (0)
; #define PG8_LDA(dst, b, h) do { _Pragma("unroll") for (int m = 0; m < 4; ++m) _Pragma("unroll") for (int k = 0; k < 2; ++k) dst[m][k] = *(const LAS bf16x8*)(lds + PG8_SA(b, h) + aoff + m * 2048 + k * 1024); } while (0)
; #define PG8_MMA(ai, bj, At, Bt) do { __builtin_amdgcn_s_setprio(1); _Pragma("unroll") for (int m = 0; m < 4; ++m) _Pragma("unroll") for (int n = 0; n < 2; ++n) _Pragma("unroll") for (int k = 0; k < 2; ++k) \
;         acc[ai][bj][m][n] = __builtin_amdgcn_mfma_f32_16x16x32_bf16(Bt[n][k], At[m][k], acc[ai][bj][m][n], 0, 0, 0); __builtin_amdgcn_s_setprio(0); } while (0)
; #define PG8_WAIT_V(n) asm volatile("s_waitcnt vmcnt(" #n ")" ::: "memory")
; #define PG8_WAIT_L(n) asm volatile("s_waitcnt lgkmcnt(" #n ")" ::: "memory")
; #define PG8_BAR __builtin_amdgcn_s_barrier()
; #define PG8_SCHED __builtin_amdgcn_sched_barrier(0)
; template <class Epi, class Sched, bool HN = false>
; __device__ __forceinline__ void gemm_phase(LAS unsigned char* lds, const Gemm g, const Sched& S, const Epi& E) {
;     ...
;         for (int t = 0; t < nt; t += 2) {
;             const bool last = (t == nt - 2);
;             const char* a1 = cA + (size_t)(t + 1) * kstep;
;             const char* a2 = last ? nA : cA + (size_t)(t + 2) * kstep; const char* b2 = last ? nB : cB + (size_t)(t + 2) * kstep;
;     ...
;             PG8_LDA(At, 1, 1); PG8_STAGE(PG8_SB(1, 0), b3, voffB); PG8_STAGE(PG8_SB(1, 1), b3 + hstep, voffB); PG8_STAGE(PG8_SA(1, 0), a3, voffA);
;             PG8_WAIT_V(8); PG8_WAIT_L(0); PG8_BAR; PG8_MMA(1, 0, At, B0); PG8_MMA(1, 1, At, B1); PG8_BAR; PG8_SCHED;
	s_add_i32 s58, s79, s63
	v_lshl_add_u64 v[174:175], v[174:175], 0, s[28:29]
	s_mov_b32 m0, s58
	ds_read_b128 v[194:197], v179 offset:49152
	ds_read_b128 v[208:211], v179 offset:50176
	ds_read_b128 v[212:215], v179 offset:51200
	ds_read_b128 v[226:229], v179 offset:52224
	ds_read_b128 v[230:233], v179 offset:53248
	ds_read_b128 v[234:237], v179 offset:54272
	ds_read_b128 v[238:241], v179 offset:55296
	ds_read_b128 v[242:245], v179 offset:56320
	global_load_lds_dwordx4 v[174:175], off
	s_add_i32 m0, s58, 0x2000
	s_add_u32 s56, s56, 0x80080
	v_lshl_add_u64 v[174:175], v[246:247], 0, s[28:29]
	s_addc_u32 s57, s57, 0
	s_add_i32 s58, s83, s63
	global_load_lds_dwordx4 v[174:175], off
	v_lshl_add_u64 v[174:175], s[56:57], 0, v[144:145]
	s_mov_b32 m0, s58
	s_nop 0
	global_load_lds_dwordx4 v[174:175], off
	v_lshl_add_u64 v[174:175], s[56:57], 0, v[148:149]
	s_add_i32 m0, s58, 0x2000
	s_nop 0
	global_load_lds_dwordx4 v[174:175], off
	v_lshl_add_u64 v[174:175], v[248:249], 0, s[28:29]
	s_mov_b32 m0, s70
	s_nop 0
	global_load_lds_dwordx4 v[174:175], off
	v_lshl_add_u64 v[174:175], v[250:251], 0, s[28:29]
	s_mov_b32 m0, s71
	s_nop 0
	global_load_lds_dwordx4 v[174:175], off
	s_waitcnt vmcnt(8)
	s_waitcnt lgkmcnt(0)
	s_barrier
	s_setprio 1
	s_waitcnt lgkmcnt(0)
	v_mfma_f32_16x16x32_bf16 v[62:65], v[130:133], v[194:197], v[62:65]
	v_mfma_f32_16x16x32_bf16 v[58:61], v[138:141], v[194:197], v[58:61]
	v_mfma_f32_16x16x32_bf16 v[46:49], v[130:133], v[212:215], v[46:49]
	v_mfma_f32_16x16x32_bf16 v[42:45], v[138:141], v[212:215], v[42:45]
	v_mfma_f32_16x16x32_bf16 v[30:33], v[130:133], v[230:233], v[30:33]
	v_mfma_f32_16x16x32_bf16 v[26:29], v[138:141], v[230:233], v[26:29]
	v_mfma_f32_16x16x32_bf16 v[12:15], v[130:133], v[238:241], v[12:15]
	v_mfma_f32_16x16x32_bf16 v[8:11], v[138:141], v[238:241], v[8:11]
	v_mfma_f32_16x16x32_bf16 v[62:65], v[134:137], v[208:211], v[62:65]
	v_mfma_f32_16x16x32_bf16 v[58:61], v[166:169], v[208:211], v[58:61]
	v_mfma_f32_16x16x32_bf16 v[46:49], v[134:137], v[226:229], v[46:49]
	v_mfma_f32_16x16x32_bf16 v[42:45], v[166:169], v[226:229], v[42:45]
	v_mfma_f32_16x16x32_bf16 v[30:33], v[134:137], v[234:237], v[30:33]
	v_mfma_f32_16x16x32_bf16 v[26:29], v[166:169], v[234:237], v[26:29]
	v_mfma_f32_16x16x32_bf16 v[12:15], v[134:137], v[242:245], v[12:15]
	v_mfma_f32_16x16x32_bf16 v[8:11], v[166:169], v[242:245], v[8:11]
	s_setprio 0
	s_setprio 1
	v_mfma_f32_16x16x32_bf16 v[54:57], v[170:173], v[194:197], v[54:57]
	v_mfma_f32_16x16x32_bf16 v[50:53], v[186:189], v[194:197], v[50:53]
	v_mfma_f32_16x16x32_bf16 v[38:41], v[170:173], v[212:215], v[38:41]
	v_mfma_f32_16x16x32_bf16 v[34:37], v[186:189], v[212:215], v[34:37]
	v_mfma_f32_16x16x32_bf16 v[20:23], v[170:173], v[230:233], v[20:23]
	v_mfma_f32_16x16x32_bf16 v[16:19], v[186:189], v[230:233], v[16:19]
	v_mfma_f32_16x16x32_bf16 v[4:7], v[170:173], v[238:241], v[4:7]
	v_mfma_f32_16x16x32_bf16 v[0:3], v[186:189], v[238:241], v[0:3]
	v_mfma_f32_16x16x32_bf16 v[54:57], v[182:185], v[208:211], v[54:57]
	v_mfma_f32_16x16x32_bf16 v[50:53], v[190:193], v[208:211], v[50:53]
	v_mfma_f32_16x16x32_bf16 v[38:41], v[182:185], v[226:229], v[38:41]
	v_mfma_f32_16x16x32_bf16 v[34:37], v[190:193], v[226:229], v[34:37]
	v_mfma_f32_16x16x32_bf16 v[20:23], v[182:185], v[234:237], v[20:23]
	v_mfma_f32_16x16x32_bf16 v[16:19], v[190:193], v[234:237], v[16:19]
	v_mfma_f32_16x16x32_bf16 v[4:7], v[182:185], v[242:245], v[4:7]
	v_mfma_f32_16x16x32_bf16 v[0:3], v[190:193], v[242:245], v[0:3]
	s_setprio 0
	s_add_i32 s78, s78, 2
	s_add_u32 s30, s30, 0x100
	s_addc_u32 s31, s31, 0
	s_add_u32 s76, s76, 0x100
	s_addc_u32 s77, s77, 0
	s_cmp_gt_u32 s78, 29
	s_barrier
	s_cbranch_scc0 .LBB0_209
	s_and_b64 vcc, exec, s[46:47]
	s_cbranch_vccz .LBB0_212
	s_barrier

; #define PG8_STAGE(bufoff, gbase, voff) do { _Pragma("unroll") for (int _i = 0; _i < 2; ++_i) \
;         __builtin_amdgcn_global_load_lds((const unsigned*)((const char*)(gbase) + (voff)[_i]), (LAS unsigned*)(lds + (bufoff) + ldsw + _i * 8192), 16, 0, 0); } while (0)
; #define PG8_LDA(dst, b, h) do { _Pragma("unroll") for (int m = 0; m < 4; ++m) _Pragma("unroll") for (int k = 0; k < 2; ++k) dst[m][k] = *(const LAS bf16x8*)(lds + PG8_SA(b, h) + aoff + m * 2048 + k * 1024); } while (0)
; #define PG8_LDB(dst, b, h) do { _Pragma("unroll") for (int n = 0; n < 2; ++n) _Pragma("unroll") for (int k = 0; k < 2; ++k) dst[n][k] = *(const LAS bf16x8*)(lds + PG8_SB(b, h) + boff + n * 2048 + k * 1024); } while (0)
; #define PG8_MMA(ai, bj, At, Bt) do { __builtin_amdgcn_s_setprio(1); _Pragma("unroll") for (int m = 0; m < 4; ++m) _Pragma("unroll") for (int n = 0; n < 2; ++n) _Pragma("unroll") for (int k = 0; k < 2; ++k) \
;         acc[ai][bj][m][n] = __builtin_amdgcn_mfma_f32_16x16x32_bf16(Bt[n][k], At[m][k], acc[ai][bj][m][n], 0, 0, 0); __builtin_amdgcn_s_setprio(0); } while (0)
; #define PG8_WAIT_V(n) asm volatile("s_waitcnt vmcnt(" #n ")" ::: "memory")
; #define PG8_WAIT_L(n) asm volatile("s_waitcnt lgkmcnt(" #n ")" ::: "memory")
; #define PG8_BAR __builtin_amdgcn_s_barrier()
; #define PG8_SCHED __builtin_amdgcn_sched_barrier(0)
; template <class Epi, class Sched, bool HN = false>
; __device__ __forceinline__ void gemm_phase(LAS unsigned char* lds, const Gemm g, const Sched& S, const Epi& E) {
;     ...
;             PG8_LDB(B0, 0, 0); PG8_SCHED; PG8_LDA(At, 0, 0); PG8_STAGE(PG8_SA(1, 1), a1 + hstep, voffA);
;             PG8_WAIT_V(6); PG8_WAIT_L(0); PG8_BAR; PG8_MMA(0, 0, At, B0); PG8_BAR; PG8_SCHED;
;             PG8_LDA(At, 0, 1); PG8_STAGE(PG8_SB(0, 0), b2, voffB); PG8_STAGE(PG8_SA(0, 0), a2, voffA);
;             PG8_WAIT_V(6); PG8_WAIT_L(0); PG8_BAR; PG8_MMA(1, 0, At, B0); PG8_BAR; PG8_SCHED;
.LBB0_1059:
	s_add_u32 s52, s50, 0xfffc0080
	s_addc_u32 s53, s51, -1
	s_add_i32 s74, 0, 0x10000
	v_add_u32_e32 v92, s74, v89
	ds_read_b128 v[26:29], v92
	ds_read_b128 v[30:33], v92 offset:1024
	ds_read_b128 v[84:87], v92 offset:2048
	ds_read_b128 v[92:95], v92 offset:3072
	s_cmp_eq_u32 s73, 12
	s_cselect_b32 s53, s31, s53
	s_cselect_b32 s52, s43, s52
	s_cselect_b32 s77, s41, s72
	s_cselect_b32 s76, s49, s71
	v_lshl_add_u64 v[128:129], s[50:51], 0, v[80:81]
	s_add_i32 m0, s60, 0xc000
	ds_read_b128 v[96:99], v91
	ds_read_b128 v[100:103], v91 offset:1024
	ds_read_b128 v[104:107], v91 offset:2048
	ds_read_b128 v[108:111], v91 offset:3072
	ds_read_b128 v[112:115], v91 offset:4096
	ds_read_b128 v[116:119], v91 offset:5120
	ds_read_b128 v[120:123], v91 offset:6144
	ds_read_b128 v[124:127], v91 offset:7168
	global_load_lds_dwordx4 v[128:129], off
	v_lshl_add_u64 v[128:129], s[50:51], 0, v[82:83]
	s_add_i32 m0, s60, 0xe000
	s_nop 0
	global_load_lds_dwordx4 v[128:129], off
	s_waitcnt vmcnt(6)
	s_waitcnt lgkmcnt(0)
	s_barrier
	s_setprio 1
	s_waitcnt lgkmcnt(0)
	v_mfma_f32_16x16x32_bf16 v[70:73], v[26:29], v[96:99], v[70:73]
	v_mfma_f32_16x16x32_bf16 v[66:69], v[84:87], v[96:99], v[66:69]
	v_mfma_f32_16x16x32_bf16 v[62:65], v[26:29], v[104:107], v[62:65]
	v_mfma_f32_16x16x32_bf16 v[58:61], v[84:87], v[104:107], v[58:61]
	v_mfma_f32_16x16x32_bf16 v[54:57], v[26:29], v[112:115], v[54:57]
	v_mfma_f32_16x16x32_bf16 v[50:53], v[84:87], v[112:115], v[50:53]
	v_mfma_f32_16x16x32_bf16 v[46:49], v[26:29], v[120:123], v[46:49]
	v_mfma_f32_16x16x32_bf16 v[42:45], v[84:87], v[120:123], v[42:45]
	v_mfma_f32_16x16x32_bf16 v[70:73], v[30:33], v[100:103], v[70:73]
	v_mfma_f32_16x16x32_bf16 v[66:69], v[92:95], v[100:103], v[66:69]
	v_mfma_f32_16x16x32_bf16 v[62:65], v[30:33], v[108:111], v[62:65]
	v_mfma_f32_16x16x32_bf16 v[58:61], v[92:95], v[108:111], v[58:61]
	v_mfma_f32_16x16x32_bf16 v[54:57], v[30:33], v[116:119], v[54:57]
	v_mfma_f32_16x16x32_bf16 v[50:53], v[92:95], v[116:119], v[50:53]
	v_mfma_f32_16x16x32_bf16 v[46:49], v[30:33], v[124:127], v[46:49]
	v_mfma_f32_16x16x32_bf16 v[42:45], v[92:95], v[124:127], v[42:45]
	s_setprio 0
	s_barrier
	s_add_i32 s74, s74, s59
	v_lshl_add_u64 v[128:129], s[76:77], 0, v[24:25]
	s_mov_b32 m0, s74
	ds_read_b128 v[96:99], v91 offset:16384
	ds_read_b128 v[100:103], v91 offset:17408
	ds_read_b128 v[104:107], v91 offset:18432
	ds_read_b128 v[108:111], v91 offset:19456
	ds_read_b128 v[112:115], v91 offset:20480
	ds_read_b128 v[116:119], v91 offset:21504
	ds_read_b128 v[120:123], v91 offset:22528
	ds_read_b128 v[124:127], v91 offset:23552
	global_load_lds_dwordx4 v[128:129], off
	v_lshl_add_u64 v[130:131], s[76:77], 0, v[78:79]
	s_add_i32 m0, s74, 0x2000
	v_lshl_add_u64 v[132:133], s[52:53], 0, v[74:75]
	global_load_lds_dwordx4 v[130:131], off
	s_mov_b32 m0, s60
	v_lshl_add_u64 v[134:135], s[52:53], 0, v[76:77]
	global_load_lds_dwordx4 v[132:133], off
	s_mov_b32 m0, s61
	s_nop 0
	global_load_lds_dwordx4 v[134:135], off
	s_waitcnt vmcnt(6)
	s_waitcnt lgkmcnt(0)
	s_barrier
	s_setprio 1
	s_waitcnt lgkmcnt(0)
	v_mfma_f32_16x16x32_bf16 v[38:41], v[26:29], v[96:99], v[38:41]
	v_mfma_f32_16x16x32_bf16 v[34:37], v[84:87], v[96:99], v[34:37]
	v_mfma_f32_16x16x32_bf16 v[20:23], v[26:29], v[104:107], v[20:23]
	v_mfma_f32_16x16x32_bf16 v[16:19], v[84:87], v[104:107], v[16:19]
	v_mfma_f32_16x16x32_bf16 v[12:15], v[26:29], v[112:115], v[12:15]
	v_mfma_f32_16x16x32_bf16 v[8:11], v[84:87], v[112:115], v[8:11]
	v_mfma_f32_16x16x32_bf16 v[4:7], v[26:29], v[120:123], v[4:7]
	v_mfma_f32_16x16x32_bf16 v[0:3], v[84:87], v[120:123], v[0:3]
	v_mfma_f32_16x16x32_bf16 v[38:41], v[30:33], v[100:103], v[38:41]
	v_mfma_f32_16x16x32_bf16 v[34:37], v[92:95], v[100:103], v[34:37]
	v_mfma_f32_16x16x32_bf16 v[20:23], v[30:33], v[108:111], v[20:23]
	v_mfma_f32_16x16x32_bf16 v[16:19], v[92:95], v[108:111], v[16:19]
	v_mfma_f32_16x16x32_bf16 v[12:15], v[30:33], v[116:119], v[12:15]
	v_mfma_f32_16x16x32_bf16 v[8:11], v[92:95], v[116:119], v[8:11]
	v_mfma_f32_16x16x32_bf16 v[4:7], v[30:33], v[124:127], v[4:7]
	v_mfma_f32_16x16x32_bf16 v[0:3], v[92:95], v[124:127], v[0:3]
	s_setprio 0
	s_barrier
; #define PG8_STAGE(bufoff, gbase, voff) do { _Pragma("unroll") for (int _i = 0; _i < 2; ++_i) \
;         __builtin_amdgcn_global_load_lds((const unsigned*)((const char*)(gbase) + (voff)[_i]), (LAS unsigned*)(lds + (bufoff) + ldsw + _i * 8192), 16, 0, 0); } while (0)
; #define PG8_LDA(dst, b, h) do { _Pragma("unroll") for (int m = 0; m < 4; ++m) _Pragma("unroll") for (int k = 0; k < 2; ++k) dst[m][k] = *(const LAS bf16x8*)(lds + PG8_SA(b, h) + aoff + m * 2048 + k * 1024); } while (0)
; #define PG8_LDB(dst, b, h) do { _Pragma("unroll") for (int n = 0; n < 2; ++n) _Pragma("unroll") for (int k = 0; k < 2; ++k) dst[n][k] = *(const LAS bf16x8*)(lds + PG8_SB(b, h) + boff + n * 2048 + k * 1024); } while (0)
; #define PG8_MMA(ai, bj, At, Bt) do { __builtin_amdgcn_s_setprio(1); _Pragma("unroll") for (int m = 0; m < 4; ++m) _Pragma("unroll") for (int n = 0; n < 2; ++n) _Pragma("unroll") for (int k = 0; k < 2; ++k) \
;         acc[ai][bj][m][n] = __builtin_amdgcn_mfma_f32_16x16x32_bf16(Bt[n][k], At[m][k], acc[ai][bj][m][n], 0, 0, 0); __builtin_amdgcn_s_setprio(0); } while (0)
; #define PG8_WAIT_V(n) asm volatile("s_waitcnt vmcnt(" #n ")" ::: "memory")
; #define PG8_WAIT_L(n) asm volatile("s_waitcnt lgkmcnt(" #n ")" ::: "memory")
; #define PG8_BAR __builtin_amdgcn_s_barrier()
; #define PG8_SCHED __builtin_amdgcn_sched_barrier(0)
; template <class Epi, class Sched, bool HN = false>
; __device__ __forceinline__ void gemm_phase(LAS unsigned char* lds, const Gemm g, const Sched& S, const Epi& E) {
;     ...
;             PG8_LDB(B0, 1, 0); PG8_SCHED; PG8_LDA(At, 1, 0); PG8_STAGE(PG8_SA(0, 1), a2 + hstep, voffA);
;             PG8_WAIT_V(6); PG8_WAIT_L(0); PG8_BAR; PG8_MMA(0, 0, At, B0); PG8_BAR; PG8_SCHED;
;             PG8_LDA(At, 1, 1); PG8_STAGE(PG8_SB(1, 0), b3, voffB); PG8_STAGE(PG8_SA(1, 0), a3, voffA);
;             PG8_WAIT_V(6); PG8_WAIT_L(0); PG8_BAR; PG8_MMA(1, 0, At, B0); PG8_BAR; PG8_SCHED;
	s_add_i32 s74, 0, 0x18000
	v_add_u32_e32 v92, s74, v89
	ds_read_b128 v[26:29], v92
	ds_read_b128 v[30:33], v92 offset:1024
	ds_read_b128 v[84:87], v92 offset:2048
	ds_read_b128 v[92:95], v92 offset:3072
	s_add_u32 s52, s52, 0x40000
	s_addc_u32 s53, s53, 0
	s_mov_b32 m0, s62
	v_lshl_add_u64 v[136:137], s[52:53], 0, v[74:75]
	ds_read_b128 v[96:99], v91 offset:32768
	ds_read_b128 v[100:103], v91 offset:33792
	ds_read_b128 v[104:107], v91 offset:34816
	ds_read_b128 v[108:111], v91 offset:35840
	ds_read_b128 v[112:115], v91 offset:36864
	ds_read_b128 v[116:119], v91 offset:37888
	ds_read_b128 v[120:123], v91 offset:38912
	ds_read_b128 v[124:127], v91 offset:39936
	global_load_lds_dwordx4 v[136:137], off
	v_lshl_add_u64 v[136:137], s[52:53], 0, v[76:77]
	s_mov_b32 m0, s63
	s_nop 0
	global_load_lds_dwordx4 v[136:137], off
	s_waitcnt vmcnt(6)
	s_waitcnt lgkmcnt(0)
	s_barrier
	s_setprio 1
	s_waitcnt lgkmcnt(0)
	v_mfma_f32_16x16x32_bf16 v[70:73], v[26:29], v[96:99], v[70:73]
	v_mfma_f32_16x16x32_bf16 v[66:69], v[84:87], v[96:99], v[66:69]
	v_mfma_f32_16x16x32_bf16 v[62:65], v[26:29], v[104:107], v[62:65]
	v_mfma_f32_16x16x32_bf16 v[58:61], v[84:87], v[104:107], v[58:61]
	v_mfma_f32_16x16x32_bf16 v[54:57], v[26:29], v[112:115], v[54:57]
	v_mfma_f32_16x16x32_bf16 v[50:53], v[84:87], v[112:115], v[50:53]
	v_mfma_f32_16x16x32_bf16 v[46:49], v[26:29], v[120:123], v[46:49]
	v_mfma_f32_16x16x32_bf16 v[42:45], v[84:87], v[120:123], v[42:45]
	v_mfma_f32_16x16x32_bf16 v[70:73], v[30:33], v[100:103], v[70:73]
	v_mfma_f32_16x16x32_bf16 v[66:69], v[92:95], v[100:103], v[66:69]
	v_mfma_f32_16x16x32_bf16 v[62:65], v[30:33], v[108:111], v[62:65]
	v_mfma_f32_16x16x32_bf16 v[58:61], v[92:95], v[108:111], v[58:61]
	v_mfma_f32_16x16x32_bf16 v[54:57], v[30:33], v[116:119], v[54:57]
	v_mfma_f32_16x16x32_bf16 v[50:53], v[92:95], v[116:119], v[50:53]
	v_mfma_f32_16x16x32_bf16 v[46:49], v[30:33], v[124:127], v[46:49]
	v_mfma_f32_16x16x32_bf16 v[42:45], v[92:95], v[124:127], v[42:45]
	s_setprio 0
	s_barrier
	s_add_i32 s52, s74, s59
	v_lshl_add_u64 v[128:129], v[128:129], 0, s[28:29]
	s_mov_b32 m0, s52
	ds_read_b128 v[96:99], v91 offset:49152
	ds_read_b128 v[100:103], v91 offset:50176
	ds_read_b128 v[104:107], v91 offset:51200
	ds_read_b128 v[108:111], v91 offset:52224
	ds_read_b128 v[112:115], v91 offset:53248
	ds_read_b128 v[116:119], v91 offset:54272
	ds_read_b128 v[120:123], v91 offset:55296
	ds_read_b128 v[124:127], v91 offset:56320
	global_load_lds_dwordx4 v[128:129], off
	v_lshl_add_u64 v[128:129], v[130:131], 0, s[28:29]
	s_add_i32 m0, s52, 0x2000
	s_nop 0
	global_load_lds_dwordx4 v[128:129], off
	v_lshl_add_u64 v[128:129], v[132:133], 0, s[28:29]
	s_mov_b32 m0, s65
	s_nop 0
	global_load_lds_dwordx4 v[128:129], off
	v_lshl_add_u64 v[128:129], v[134:135], 0, s[28:29]
	s_mov_b32 m0, s66
	s_nop 0
	global_load_lds_dwordx4 v[128:129], off
	s_waitcnt vmcnt(6)
	s_waitcnt lgkmcnt(0)
	s_barrier
	s_setprio 1
	s_waitcnt lgkmcnt(0)
	v_mfma_f32_16x16x32_bf16 v[38:41], v[26:29], v[96:99], v[38:41]
	v_mfma_f32_16x16x32_bf16 v[34:37], v[84:87], v[96:99], v[34:37]
	v_mfma_f32_16x16x32_bf16 v[20:23], v[26:29], v[104:107], v[20:23]
	v_mfma_f32_16x16x32_bf16 v[16:19], v[84:87], v[104:107], v[16:19]
	v_mfma_f32_16x16x32_bf16 v[12:15], v[26:29], v[112:115], v[12:15]
	v_mfma_f32_16x16x32_bf16 v[8:11], v[84:87], v[112:115], v[8:11]
	v_mfma_f32_16x16x32_bf16 v[4:7], v[26:29], v[120:123], v[4:7]
	v_mfma_f32_16x16x32_bf16 v[0:3], v[84:87], v[120:123], v[0:3]
	v_mfma_f32_16x16x32_bf16 v[38:41], v[30:33], v[100:103], v[38:41]
	v_mfma_f32_16x16x32_bf16 v[34:37], v[92:95], v[100:103], v[34:37]
	v_mfma_f32_16x16x32_bf16 v[20:23], v[30:33], v[108:111], v[20:23]
	v_mfma_f32_16x16x32_bf16 v[16:19], v[92:95], v[108:111], v[16:19]
	v_mfma_f32_16x16x32_bf16 v[12:15], v[30:33], v[116:119], v[12:15]
	v_mfma_f32_16x16x32_bf16 v[8:11], v[92:95], v[116:119], v[8:11]
	v_mfma_f32_16x16x32_bf16 v[4:7], v[30:33], v[124:127], v[4:7]
	v_mfma_f32_16x16x32_bf16 v[0:3], v[92:95], v[124:127], v[0:3]
	s_setprio 0
	s_add_i32 s73, s73, 2
	s_add_u32 s50, s50, 0x100
	s_addc_u32 s51, s51, 0
	s_add_u32 s71, s71, 0x100
	s_addc_u32 s72, s72, 0
	s_cmp_gt_u32 s73, 13
	s_barrier
	s_cbranch_scc0 .LBB0_1059
	s_and_b64 vcc, exec, s[34:35]
	s_cbranch_vccz .LBB0_1062
	s_barrier

; #define PG8_STAGE(bufoff, gbase, voff) do { _Pragma("unroll") for (int _i = 0; _i < 2; ++_i) \
;         __builtin_amdgcn_global_load_lds((const unsigned*)((const char*)(gbase) + (voff)[_i]), (LAS unsigned*)(lds + (bufoff) + ldsw + _i * 8192), 16, 0, 0); } while (0)
; #define PG8_LDA(dst, b, h) do { _Pragma("unroll") for (int m = 0; m < 4; ++m) _Pragma("unroll") for (int k = 0; k < 2; ++k) dst[m][k] = *(const LAS bf16x8*)(lds + PG8_SA(b, h) + aoff + m * 2048 + k * 1024); } while (0)
; #define PG8_LDB(dst, b, h) do { _Pragma("unroll") for (int n = 0; n < 2; ++n) _Pragma("unroll") for (int k = 0; k < 2; ++k) dst[n][k] = *(const LAS bf16x8*)(lds + PG8_SB(b, h) + boff + n * 2048 + k * 1024); } while (0)
; #define PG8_MMA(ai, bj, At, Bt) do { __builtin_amdgcn_s_setprio(1); _Pragma("unroll") for (int m = 0; m < 4; ++m) _Pragma("unroll") for (int n = 0; n < 2; ++n) _Pragma("unroll") for (int k = 0; k < 2; ++k) \
;         acc[ai][bj][m][n] = __builtin_amdgcn_mfma_f32_16x16x32_bf16(Bt[n][k], At[m][k], acc[ai][bj][m][n], 0, 0, 0); __builtin_amdgcn_s_setprio(0); } while (0)
; #define PG8_WAIT_V(n) asm volatile("s_waitcnt vmcnt(" #n ")" ::: "memory")
; #define PG8_WAIT_L(n) asm volatile("s_waitcnt lgkmcnt(" #n ")" ::: "memory")
; #define PG8_BAR __builtin_amdgcn_s_barrier()
; #define PG8_SCHED __builtin_amdgcn_sched_barrier(0)
; template <class Epi, class Sched, bool HN = false>
; __device__ __forceinline__ void gemm_phase(LAS unsigned char* lds, const Gemm g, const Sched& S, const Epi& E) {
;     ...
;             PG8_LDB(B0, 0, 0); PG8_LDB(B1, 0, 1); PG8_SCHED; PG8_LDA(At, 0, 0); PG8_STAGE(PG8_SA(1, 1), a1 + hstep, voffA);
;             PG8_WAIT_V(8); PG8_WAIT_L(0); PG8_BAR; PG8_MMA(0, 0, At, B0); PG8_MMA(0, 1, At, B1); PG8_BAR; PG8_SCHED;
;             PG8_LDA(At, 0, 1); PG8_STAGE(PG8_SB(0, 0), b2, voffB); PG8_STAGE(PG8_SB(0, 1), b2 + hstep, voffB); PG8_STAGE(PG8_SA(0, 0), a2, voffA);
.LBB0_1271:
	s_add_u32 s52, s30, 0xfff80080
	s_addc_u32 s53, s31, -1
	s_add_i32 s72, 0, 0x10000
	s_cmp_eq_u32 s71, 28
	s_cselect_b32 s55, s39, s53
	s_cselect_b32 s54, s47, s52
	s_cselect_b32 s53, s45, s70
	s_cselect_b32 s52, s66, s67
	s_add_i32 s74, 0, 0x14000
	v_add_u32_e32 v152, s72, v164
	v_add_u32_e32 v160, s74, v164
	ds_read_b128 v[130:133], v152
	ds_read_b128 v[134:137], v152 offset:1024
	ds_read_b128 v[138:141], v152 offset:2048
	ds_read_b128 v[152:155], v152 offset:3072
	ds_read_b128 v[156:159], v160
	ds_read_b128 v[168:171], v160 offset:1024
	ds_read_b128 v[172:175], v160 offset:2048
	ds_read_b128 v[176:179], v160 offset:3072
	v_lshl_add_u64 v[160:161], s[30:31], 0, v[148:149]
	s_add_i32 m0, s57, 0xc000
	ds_read_b128 v[180:183], v166
	ds_read_b128 v[184:187], v166 offset:1024
	ds_read_b128 v[188:191], v166 offset:2048
	ds_read_b128 v[192:195], v166 offset:3072
	ds_read_b128 v[208:211], v166 offset:4096
	ds_read_b128 v[212:215], v166 offset:5120
	ds_read_b128 v[226:229], v166 offset:6144
	ds_read_b128 v[230:233], v166 offset:7168
	global_load_lds_dwordx4 v[160:161], off
	v_lshl_add_u64 v[160:161], s[30:31], 0, v[150:151]
	s_add_i32 m0, s57, 0xe000
	s_nop 0
	global_load_lds_dwordx4 v[160:161], off
	s_waitcnt vmcnt(8)
	s_waitcnt lgkmcnt(0)
	s_barrier
	s_setprio 1
	s_waitcnt lgkmcnt(0)
	v_mfma_f32_16x16x32_bf16 v[126:129], v[130:133], v[180:183], v[126:129]
	v_mfma_f32_16x16x32_bf16 v[122:125], v[138:141], v[180:183], v[122:125]
	v_mfma_f32_16x16x32_bf16 v[110:113], v[130:133], v[188:191], v[110:113]
	v_mfma_f32_16x16x32_bf16 v[106:109], v[138:141], v[188:191], v[106:109]
	v_mfma_f32_16x16x32_bf16 v[94:97], v[130:133], v[208:211], v[94:97]
	v_mfma_f32_16x16x32_bf16 v[90:93], v[138:141], v[208:211], v[90:93]
	v_mfma_f32_16x16x32_bf16 v[78:81], v[130:133], v[226:229], v[78:81]
	v_mfma_f32_16x16x32_bf16 v[74:77], v[138:141], v[226:229], v[74:77]
	v_mfma_f32_16x16x32_bf16 v[126:129], v[134:137], v[184:187], v[126:129]
	v_mfma_f32_16x16x32_bf16 v[122:125], v[152:155], v[184:187], v[122:125]
	v_mfma_f32_16x16x32_bf16 v[110:113], v[134:137], v[192:195], v[110:113]
	v_mfma_f32_16x16x32_bf16 v[106:109], v[152:155], v[192:195], v[106:109]
	v_mfma_f32_16x16x32_bf16 v[94:97], v[134:137], v[212:215], v[94:97]
	v_mfma_f32_16x16x32_bf16 v[90:93], v[152:155], v[212:215], v[90:93]
	v_mfma_f32_16x16x32_bf16 v[78:81], v[134:137], v[230:233], v[78:81]
	v_mfma_f32_16x16x32_bf16 v[74:77], v[152:155], v[230:233], v[74:77]
	s_setprio 0
	s_setprio 1
	v_mfma_f32_16x16x32_bf16 v[118:121], v[156:159], v[180:183], v[118:121]
	v_mfma_f32_16x16x32_bf16 v[114:117], v[172:175], v[180:183], v[114:117]
	v_mfma_f32_16x16x32_bf16 v[102:105], v[156:159], v[188:191], v[102:105]
	v_mfma_f32_16x16x32_bf16 v[98:101], v[172:175], v[188:191], v[98:101]
	v_mfma_f32_16x16x32_bf16 v[86:89], v[156:159], v[208:211], v[86:89]
	v_mfma_f32_16x16x32_bf16 v[82:85], v[172:175], v[208:211], v[82:85]
	v_mfma_f32_16x16x32_bf16 v[70:73], v[156:159], v[226:229], v[70:73]
	v_mfma_f32_16x16x32_bf16 v[66:69], v[172:175], v[226:229], v[66:69]
	v_mfma_f32_16x16x32_bf16 v[118:121], v[168:171], v[184:187], v[118:121]
	v_mfma_f32_16x16x32_bf16 v[114:117], v[176:179], v[184:187], v[114:117]
	v_mfma_f32_16x16x32_bf16 v[102:105], v[168:171], v[192:195], v[102:105]
	v_mfma_f32_16x16x32_bf16 v[98:101], v[176:179], v[192:195], v[98:101]
	v_mfma_f32_16x16x32_bf16 v[86:89], v[168:171], v[212:215], v[86:89]
	v_mfma_f32_16x16x32_bf16 v[82:85], v[176:179], v[212:215], v[82:85]
	v_mfma_f32_16x16x32_bf16 v[70:73], v[168:171], v[230:233], v[70:73]
	v_mfma_f32_16x16x32_bf16 v[66:69], v[176:179], v[230:233], v[66:69]
	s_setprio 0
	s_barrier
	s_add_i32 s72, s72, s56
	v_lshl_add_u64 v[160:161], s[52:53], 0, v[24:25]
	s_mov_b32 m0, s72
	ds_read_b128 v[180:183], v166 offset:16384
	ds_read_b128 v[184:187], v166 offset:17408
	ds_read_b128 v[188:191], v166 offset:18432
	ds_read_b128 v[192:195], v166 offset:19456
	ds_read_b128 v[208:211], v166 offset:20480
	ds_read_b128 v[212:215], v166 offset:21504
	ds_read_b128 v[226:229], v166 offset:22528
	ds_read_b128 v[230:233], v166 offset:23552
	global_load_lds_dwordx4 v[160:161], off
	s_add_i32 m0, s72, 0x2000
	s_add_u32 s72, s52, 0x80000
	v_lshl_add_u64 v[196:197], s[52:53], 0, v[146:147]
	s_addc_u32 s73, s53, 0
	s_add_i32 s74, s74, s56
	global_load_lds_dwordx4 v[196:197], off
	v_lshl_add_u64 v[206:207], s[72:73], 0, v[24:25]
	s_mov_b32 m0, s74
	v_lshl_add_u64 v[216:217], s[54:55], 0, v[144:145]
	global_load_lds_dwordx4 v[206:207], off
	v_lshl_add_u64 v[206:207], s[72:73], 0, v[146:147]
	s_add_i32 m0, s74, 0x2000
	s_nop 0
	global_load_lds_dwordx4 v[206:207], off
	v_lshl_add_u64 v[206:207], s[54:55], 0, v[142:143]
	s_mov_b32 m0, s57
	s_nop 0
	global_load_lds_dwordx4 v[206:207], off
	s_mov_b32 m0, s58
	s_nop 0
	global_load_lds_dwordx4 v[216:217], off
	s_waitcnt vmcnt(8)
	s_waitcnt lgkmcnt(0)
	s_barrier
; #define PG8_STAGE(bufoff, gbase, voff) do { _Pragma("unroll") for (int _i = 0; _i < 2; ++_i) \
;         __builtin_amdgcn_global_load_lds((const unsigned*)((const char*)(gbase) + (voff)[_i]), (LAS unsigned*)(lds + (bufoff) + ldsw + _i * 8192), 16, 0, 0); } while (0)
; #define PG8_LDA(dst, b, h) do { _Pragma("unroll") for (int m = 0; m < 4; ++m) _Pragma("unroll") for (int k = 0; k < 2; ++k) dst[m][k] = *(const LAS bf16x8*)(lds + PG8_SA(b, h) + aoff + m * 2048 + k * 1024); } while (0)
; #define PG8_LDB(dst, b, h) do { _Pragma("unroll") for (int n = 0; n < 2; ++n) _Pragma("unroll") for (int k = 0; k < 2; ++k) dst[n][k] = *(const LAS bf16x8*)(lds + PG8_SB(b, h) + boff + n * 2048 + k * 1024); } while (0)
; #define PG8_MMA(ai, bj, At, Bt) do { __builtin_amdgcn_s_setprio(1); _Pragma("unroll") for (int m = 0; m < 4; ++m) _Pragma("unroll") for (int n = 0; n < 2; ++n) _Pragma("unroll") for (int k = 0; k < 2; ++k) \
;         acc[ai][bj][m][n] = __builtin_amdgcn_mfma_f32_16x16x32_bf16(Bt[n][k], At[m][k], acc[ai][bj][m][n], 0, 0, 0); __builtin_amdgcn_s_setprio(0); } while (0)
; #define PG8_WAIT_V(n) asm volatile("s_waitcnt vmcnt(" #n ")" ::: "memory")
; #define PG8_WAIT_L(n) asm volatile("s_waitcnt lgkmcnt(" #n ")" ::: "memory")
; #define PG8_BAR __builtin_amdgcn_s_barrier()
; #define PG8_SCHED __builtin_amdgcn_sched_barrier(0)
; template <class Epi, class Sched, bool HN = false>
; __device__ __forceinline__ void gemm_phase(LAS unsigned char* lds, const Gemm g, const Sched& S, const Epi& E) {
;     ...
;             PG8_WAIT_V(8); PG8_WAIT_L(0); PG8_BAR; PG8_MMA(1, 0, At, B0); PG8_MMA(1, 1, At, B1); PG8_BAR; PG8_SCHED;
;             PG8_LDB(B0, 1, 0); PG8_LDB(B1, 1, 1); PG8_SCHED; PG8_LDA(At, 1, 0); PG8_STAGE(PG8_SA(0, 1), a2 + hstep, voffA);
;             PG8_WAIT_V(8); PG8_WAIT_L(0); PG8_BAR; PG8_MMA(0, 0, At, B0); PG8_MMA(0, 1, At, B1); PG8_BAR; PG8_SCHED;
	s_setprio 1
	s_waitcnt lgkmcnt(0)
	v_mfma_f32_16x16x32_bf16 v[62:65], v[130:133], v[180:183], v[62:65]
	v_mfma_f32_16x16x32_bf16 v[58:61], v[138:141], v[180:183], v[58:61]
	v_mfma_f32_16x16x32_bf16 v[46:49], v[130:133], v[188:191], v[46:49]
	v_mfma_f32_16x16x32_bf16 v[42:45], v[138:141], v[188:191], v[42:45]
	v_mfma_f32_16x16x32_bf16 v[30:33], v[130:133], v[208:211], v[30:33]
	v_mfma_f32_16x16x32_bf16 v[26:29], v[138:141], v[208:211], v[26:29]
	v_mfma_f32_16x16x32_bf16 v[12:15], v[130:133], v[226:229], v[12:15]
	v_mfma_f32_16x16x32_bf16 v[8:11], v[138:141], v[226:229], v[8:11]
	v_mfma_f32_16x16x32_bf16 v[62:65], v[134:137], v[184:187], v[62:65]
	v_mfma_f32_16x16x32_bf16 v[58:61], v[152:155], v[184:187], v[58:61]
	v_mfma_f32_16x16x32_bf16 v[46:49], v[134:137], v[192:195], v[46:49]
	v_mfma_f32_16x16x32_bf16 v[42:45], v[152:155], v[192:195], v[42:45]
	v_mfma_f32_16x16x32_bf16 v[30:33], v[134:137], v[212:215], v[30:33]
	v_mfma_f32_16x16x32_bf16 v[26:29], v[152:155], v[212:215], v[26:29]
	v_mfma_f32_16x16x32_bf16 v[12:15], v[134:137], v[230:233], v[12:15]
	v_mfma_f32_16x16x32_bf16 v[8:11], v[152:155], v[230:233], v[8:11]
	s_setprio 0
	s_setprio 1
	v_mfma_f32_16x16x32_bf16 v[54:57], v[156:159], v[180:183], v[54:57]
	v_mfma_f32_16x16x32_bf16 v[50:53], v[172:175], v[180:183], v[50:53]
	v_mfma_f32_16x16x32_bf16 v[38:41], v[156:159], v[188:191], v[38:41]
	v_mfma_f32_16x16x32_bf16 v[34:37], v[172:175], v[188:191], v[34:37]
	v_mfma_f32_16x16x32_bf16 v[20:23], v[156:159], v[208:211], v[20:23]
	v_mfma_f32_16x16x32_bf16 v[16:19], v[172:175], v[208:211], v[16:19]
	v_mfma_f32_16x16x32_bf16 v[4:7], v[156:159], v[226:229], v[4:7]
	v_mfma_f32_16x16x32_bf16 v[0:3], v[172:175], v[226:229], v[0:3]
	v_mfma_f32_16x16x32_bf16 v[54:57], v[168:171], v[184:187], v[54:57]
	v_mfma_f32_16x16x32_bf16 v[50:53], v[176:179], v[184:187], v[50:53]
	v_mfma_f32_16x16x32_bf16 v[38:41], v[168:171], v[192:195], v[38:41]
	v_mfma_f32_16x16x32_bf16 v[34:37], v[176:179], v[192:195], v[34:37]
	v_mfma_f32_16x16x32_bf16 v[20:23], v[168:171], v[212:215], v[20:23]
	v_mfma_f32_16x16x32_bf16 v[16:19], v[176:179], v[212:215], v[16:19]
	v_mfma_f32_16x16x32_bf16 v[4:7], v[168:171], v[230:233], v[4:7]
	v_mfma_f32_16x16x32_bf16 v[0:3], v[176:179], v[230:233], v[0:3]
	s_setprio 0
	s_barrier
	s_add_i32 s72, 0, 0x18000
	s_add_i32 s73, 0, 0x1c000
	v_add_u32_e32 v152, s72, v164
	v_add_u32_e32 v167, s73, v164
	ds_read_b128 v[130:133], v152
	ds_read_b128 v[134:137], v152 offset:1024
	ds_read_b128 v[138:141], v152 offset:2048
	ds_read_b128 v[152:155], v152 offset:3072
	ds_read_b128 v[156:159], v167
	ds_read_b128 v[168:171], v167 offset:1024
	ds_read_b128 v[172:175], v167 offset:2048
	ds_read_b128 v[176:179], v167 offset:3072
	s_add_u32 s54, s54, 0x80000
	s_addc_u32 s55, s55, 0
	s_mov_b32 m0, s59
	v_lshl_add_u64 v[234:235], s[54:55], 0, v[142:143]
	ds_read_b128 v[180:183], v166 offset:32768
	ds_read_b128 v[184:187], v166 offset:33792
	ds_read_b128 v[188:191], v166 offset:34816
	ds_read_b128 v[192:195], v166 offset:35840
	ds_read_b128 v[208:211], v166 offset:36864
	ds_read_b128 v[212:215], v166 offset:37888
	ds_read_b128 v[226:229], v166 offset:38912
	ds_read_b128 v[230:233], v166 offset:39936
	global_load_lds_dwordx4 v[234:235], off
	v_lshl_add_u64 v[234:235], s[54:55], 0, v[144:145]
	s_mov_b32 m0, s60
	s_nop 0
	global_load_lds_dwordx4 v[234:235], off
	s_waitcnt vmcnt(8)
	s_waitcnt lgkmcnt(0)
	s_barrier
	s_setprio 1
	s_waitcnt lgkmcnt(0)
	v_mfma_f32_16x16x32_bf16 v[126:129], v[130:133], v[180:183], v[126:129]
	v_mfma_f32_16x16x32_bf16 v[122:125], v[138:141], v[180:183], v[122:125]
	v_mfma_f32_16x16x32_bf16 v[110:113], v[130:133], v[188:191], v[110:113]
	v_mfma_f32_16x16x32_bf16 v[106:109], v[138:141], v[188:191], v[106:109]
	v_mfma_f32_16x16x32_bf16 v[94:97], v[130:133], v[208:211], v[94:97]
	v_mfma_f32_16x16x32_bf16 v[90:93], v[138:141], v[208:211], v[90:93]
	v_mfma_f32_16x16x32_bf16 v[78:81], v[130:133], v[226:229], v[78:81]
	v_mfma_f32_16x16x32_bf16 v[74:77], v[138:141], v[226:229], v[74:77]
	v_mfma_f32_16x16x32_bf16 v[126:129], v[134:137], v[184:187], v[126:129]
	v_mfma_f32_16x16x32_bf16 v[122:125], v[152:155], v[184:187], v[122:125]
	v_mfma_f32_16x16x32_bf16 v[110:113], v[134:137], v[192:195], v[110:113]
	v_mfma_f32_16x16x32_bf16 v[106:109], v[152:155], v[192:195], v[106:109]
	v_mfma_f32_16x16x32_bf16 v[94:97], v[134:137], v[212:215], v[94:97]
	v_mfma_f32_16x16x32_bf16 v[90:93], v[152:155], v[212:215], v[90:93]
	v_mfma_f32_16x16x32_bf16 v[78:81], v[134:137], v[230:233], v[78:81]
	v_mfma_f32_16x16x32_bf16 v[74:77], v[152:155], v[230:233], v[74:77]
	s_setprio 0
	s_setprio 1
	v_mfma_f32_16x16x32_bf16 v[118:121], v[156:159], v[180:183], v[118:121]
	v_mfma_f32_16x16x32_bf16 v[114:117], v[172:175], v[180:183], v[114:117]
	v_mfma_f32_16x16x32_bf16 v[102:105], v[156:159], v[188:191], v[102:105]
	v_mfma_f32_16x16x32_bf16 v[98:101], v[172:175], v[188:191], v[98:101]
	v_mfma_f32_16x16x32_bf16 v[86:89], v[156:159], v[208:211], v[86:89]
	v_mfma_f32_16x16x32_bf16 v[82:85], v[172:175], v[208:211], v[82:85]
	v_mfma_f32_16x16x32_bf16 v[70:73], v[156:159], v[226:229], v[70:73]
	v_mfma_f32_16x16x32_bf16 v[66:69], v[172:175], v[226:229], v[66:69]
	v_mfma_f32_16x16x32_bf16 v[118:121], v[168:171], v[184:187], v[118:121]
	v_mfma_f32_16x16x32_bf16 v[114:117], v[176:179], v[184:187], v[114:117]
	v_mfma_f32_16x16x32_bf16 v[102:105], v[168:171], v[192:195], v[102:105]
	v_mfma_f32_16x16x32_bf16 v[98:101], v[176:179], v[192:195], v[98:101]
	v_mfma_f32_16x16x32_bf16 v[86:89], v[168:171], v[212:215], v[86:89]
	v_mfma_f32_16x16x32_bf16 v[82:85], v[176:179], v[212:215], v[82:85]
	v_mfma_f32_16x16x32_bf16 v[70:73], v[168:171], v[230:233], v[70:73]
	v_mfma_f32_16x16x32_bf16 v[66:69], v[176:179], v[230:233], v[66:69]
	s_setprio 0
	s_barrier
; #define PG8_STAGE(bufoff, gbase, voff) do { _Pragma("unroll") for (int _i = 0; _i < 2; ++_i) \
;         __builtin_amdgcn_global_load_lds((const unsigned*)((const char*)(gbase) + (voff)[_i]), (LAS unsigned*)(lds + (bufoff) + ldsw + _i * 8192), 16, 0, 0); } while (0)
; #define PG8_LDA(dst, b, h) do { _Pragma("unroll") for (int m = 0; m < 4; ++m) _Pragma("unroll") for (int k = 0; k < 2; ++k) dst[m][k] = *(const LAS bf16x8*)(lds + PG8_SA(b, h) + aoff + m * 2048 + k * 1024); } while (0)
; #define PG8_MMA(ai, bj, At, Bt) do { __builtin_amdgcn_s_setprio(1); _Pragma("unroll") for (int m = 0; m < 4; ++m) _Pragma("unroll") for (int n = 0; n < 2; ++n) _Pragma("unroll") for (int k = 0; k < 2; ++k) \
;         acc[ai][bj][m][n] = __builtin_amdgcn_mfma_f32_16x16x32_bf16(Bt[n][k], At[m][k], acc[ai][bj][m][n], 0, 0, 0); __builtin_amdgcn_s_setprio(0); } while (0)
; #define PG8_WAIT_V(n) asm volatile("s_waitcnt vmcnt(" #n ")" ::: "memory")
; #define PG8_WAIT_L(n) asm volatile("s_waitcnt lgkmcnt(" #n ")" ::: "memory")
; #define PG8_BAR __builtin_amdgcn_s_barrier()
; #define PG8_SCHED __builtin_amdgcn_sched_barrier(0)
; template <class Epi, class Sched, bool HN = false>
; __device__ __forceinline__ void gemm_phase(LAS unsigned char* lds, const Gemm g, const Sched& S, const Epi& E) {
;     ...
;         for (int t = 0; t < nt; t += 2) {
;             const bool last = (t == nt - 2);
;             const char* a1 = cA + (size_t)(t + 1) * kstep;
;             const char* a2 = last ? nA : cA + (size_t)(t + 2) * kstep; const char* b2 = last ? nB : cB + (size_t)(t + 2) * kstep;
;     ...
;             PG8_LDA(At, 1, 1); PG8_STAGE(PG8_SB(1, 0), b3, voffB); PG8_STAGE(PG8_SB(1, 1), b3 + hstep, voffB); PG8_STAGE(PG8_SA(1, 0), a3, voffA);
;             PG8_WAIT_V(8); PG8_WAIT_L(0); PG8_BAR; PG8_MMA(1, 0, At, B0); PG8_MMA(1, 1, At, B1); PG8_BAR; PG8_SCHED;
	s_add_i32 s54, s72, s56
	v_lshl_add_u64 v[160:161], v[160:161], 0, s[28:29]
	s_mov_b32 m0, s54
	ds_read_b128 v[180:183], v166 offset:49152
	ds_read_b128 v[184:187], v166 offset:50176
	ds_read_b128 v[188:191], v166 offset:51200
	ds_read_b128 v[192:195], v166 offset:52224
	ds_read_b128 v[208:211], v166 offset:53248
	ds_read_b128 v[212:215], v166 offset:54272
	ds_read_b128 v[226:229], v166 offset:55296
	ds_read_b128 v[230:233], v166 offset:56320
	global_load_lds_dwordx4 v[160:161], off
	s_add_i32 m0, s54, 0x2000
	s_add_u32 s52, s52, 0x80080
	v_lshl_add_u64 v[160:161], v[196:197], 0, s[28:29]
	s_addc_u32 s53, s53, 0
	s_add_i32 s54, s73, s56
	global_load_lds_dwordx4 v[160:161], off
	v_lshl_add_u64 v[160:161], s[52:53], 0, v[24:25]
	s_mov_b32 m0, s54
	s_nop 0
	global_load_lds_dwordx4 v[160:161], off
	v_lshl_add_u64 v[160:161], s[52:53], 0, v[146:147]
	s_add_i32 m0, s54, 0x2000
	s_nop 0
	global_load_lds_dwordx4 v[160:161], off
	v_lshl_add_u64 v[160:161], v[206:207], 0, s[28:29]
	s_mov_b32 m0, s62
	s_nop 0
	global_load_lds_dwordx4 v[160:161], off
	v_lshl_add_u64 v[160:161], v[216:217], 0, s[28:29]
	s_mov_b32 m0, s63
	s_nop 0
	global_load_lds_dwordx4 v[160:161], off
	s_waitcnt vmcnt(8)
	s_waitcnt lgkmcnt(0)
	s_barrier
	s_setprio 1
	s_waitcnt lgkmcnt(0)
	v_mfma_f32_16x16x32_bf16 v[62:65], v[130:133], v[180:183], v[62:65]
	v_mfma_f32_16x16x32_bf16 v[58:61], v[138:141], v[180:183], v[58:61]
	v_mfma_f32_16x16x32_bf16 v[46:49], v[130:133], v[188:191], v[46:49]
	v_mfma_f32_16x16x32_bf16 v[42:45], v[138:141], v[188:191], v[42:45]
	v_mfma_f32_16x16x32_bf16 v[30:33], v[130:133], v[208:211], v[30:33]
	v_mfma_f32_16x16x32_bf16 v[26:29], v[138:141], v[208:211], v[26:29]
	v_mfma_f32_16x16x32_bf16 v[12:15], v[130:133], v[226:229], v[12:15]
	v_mfma_f32_16x16x32_bf16 v[8:11], v[138:141], v[226:229], v[8:11]
	v_mfma_f32_16x16x32_bf16 v[62:65], v[134:137], v[184:187], v[62:65]
	v_mfma_f32_16x16x32_bf16 v[58:61], v[152:155], v[184:187], v[58:61]
	v_mfma_f32_16x16x32_bf16 v[46:49], v[134:137], v[192:195], v[46:49]
	v_mfma_f32_16x16x32_bf16 v[42:45], v[152:155], v[192:195], v[42:45]
	v_mfma_f32_16x16x32_bf16 v[30:33], v[134:137], v[212:215], v[30:33]
	v_mfma_f32_16x16x32_bf16 v[26:29], v[152:155], v[212:215], v[26:29]
	v_mfma_f32_16x16x32_bf16 v[12:15], v[134:137], v[230:233], v[12:15]
	v_mfma_f32_16x16x32_bf16 v[8:11], v[152:155], v[230:233], v[8:11]
	s_setprio 0
	s_setprio 1
	v_mfma_f32_16x16x32_bf16 v[54:57], v[156:159], v[180:183], v[54:57]
	v_mfma_f32_16x16x32_bf16 v[50:53], v[172:175], v[180:183], v[50:53]
	v_mfma_f32_16x16x32_bf16 v[38:41], v[156:159], v[188:191], v[38:41]
	v_mfma_f32_16x16x32_bf16 v[34:37], v[172:175], v[188:191], v[34:37]
	v_mfma_f32_16x16x32_bf16 v[20:23], v[156:159], v[208:211], v[20:23]
	v_mfma_f32_16x16x32_bf16 v[16:19], v[172:175], v[208:211], v[16:19]
	v_mfma_f32_16x16x32_bf16 v[4:7], v[156:159], v[226:229], v[4:7]
	v_mfma_f32_16x16x32_bf16 v[0:3], v[172:175], v[226:229], v[0:3]
	v_mfma_f32_16x16x32_bf16 v[54:57], v[168:171], v[184:187], v[54:57]
	v_mfma_f32_16x16x32_bf16 v[50:53], v[176:179], v[184:187], v[50:53]
	v_mfma_f32_16x16x32_bf16 v[38:41], v[168:171], v[192:195], v[38:41]
	v_mfma_f32_16x16x32_bf16 v[34:37], v[176:179], v[192:195], v[34:37]
	v_mfma_f32_16x16x32_bf16 v[20:23], v[168:171], v[212:215], v[20:23]
	v_mfma_f32_16x16x32_bf16 v[16:19], v[176:179], v[212:215], v[16:19]
	v_mfma_f32_16x16x32_bf16 v[4:7], v[168:171], v[230:233], v[4:7]
	v_mfma_f32_16x16x32_bf16 v[0:3], v[176:179], v[230:233], v[0:3]
	s_setprio 0
	s_add_i32 s71, s71, 2
	s_add_u32 s30, s30, 0x100
	s_addc_u32 s31, s31, 0
	s_add_u32 s67, s67, 0x100
	s_addc_u32 s70, s70, 0
	s_cmp_gt_u32 s71, 29
	s_barrier
	s_cbranch_scc0 .LBB0_1271
	s_and_b64 vcc, exec, s[42:43]
	s_cbranch_vccz .LBB0_1274
	s_barrier

; #define PG8_STAGE(bufoff, gbase, voff) do { _Pragma("unroll") for (int _i = 0; _i < 2; ++_i) \
;         __builtin_amdgcn_global_load_lds((const unsigned*)((const char*)(gbase) + (voff)[_i]), (LAS unsigned*)(lds + (bufoff) + ldsw + _i * 8192), 16, 0, 0); } while (0)
; #define PG8_LDA(dst, b, h) do { _Pragma("unroll") for (int m = 0; m < 4; ++m) _Pragma("unroll") for (int k = 0; k < 2; ++k) dst[m][k] = *(const LAS bf16x8*)(lds + PG8_SA(b, h) + aoff + m * 2048 + k * 1024); } while (0)
; #define PG8_LDB(dst, b, h) do { _Pragma("unroll") for (int n = 0; n < 2; ++n) _Pragma("unroll") for (int k = 0; k < 2; ++k) dst[n][k] = *(const LAS bf16x8*)(lds + PG8_SB(b, h) + boff + n * 2048 + k * 1024); } while (0)
; #define PG8_MMA(ai, bj, At, Bt) do { __builtin_amdgcn_s_setprio(1); _Pragma("unroll") for (int m = 0; m < 4; ++m) _Pragma("unroll") for (int n = 0; n < 2; ++n) _Pragma("unroll") for (int k = 0; k < 2; ++k) \
;         acc[ai][bj][m][n] = __builtin_amdgcn_mfma_f32_16x16x32_bf16(Bt[n][k], At[m][k], acc[ai][bj][m][n], 0, 0, 0); __builtin_amdgcn_s_setprio(0); } while (0)
; #define PG8_WAIT_V(n) asm volatile("s_waitcnt vmcnt(" #n ")" ::: "memory")
; #define PG8_WAIT_L(n) asm volatile("s_waitcnt lgkmcnt(" #n ")" ::: "memory")
; #define PG8_BAR __builtin_amdgcn_s_barrier()
; #define PG8_SCHED __builtin_amdgcn_sched_barrier(0)
; template <class Epi, class Sched, bool HN = false>
; __device__ __forceinline__ void gemm_phase(LAS unsigned char* lds, const Gemm g, const Sched& S, const Epi& E) {
;     ...
;             PG8_LDB(B0, 0, 0); PG8_LDB(B1, 0, 1); PG8_SCHED; PG8_LDA(At, 0, 0); PG8_STAGE(PG8_SA(1, 1), a1 + hstep, voffA);
;             PG8_WAIT_V(8); PG8_WAIT_L(0); PG8_BAR; PG8_MMA(0, 0, At, B0); PG8_MMA(0, 1, At, B1); PG8_BAR; PG8_SCHED;
;             PG8_LDA(At, 0, 1); PG8_STAGE(PG8_SB(0, 0), b2, voffB); PG8_STAGE(PG8_SB(0, 1), b2 + hstep, voffB); PG8_STAGE(PG8_SA(0, 0), a2, voffA);
.LBB0_1357:
	s_add_u32 s58, s30, 0xffe00080
	s_addc_u32 s59, s31, -1
	s_add_i32 s86, 0, 0x10000
	s_cmpk_eq_i32 s85, 0x7c
	s_cselect_b32 s61, s43, s59
	s_cselect_b32 s60, s45, s58
	v_add_u32_e32 v148, s86, v151
	s_cselect_b32 s59, s51, s84
	s_cselect_b32 s58, s53, s74
	s_add_i32 vcc_lo, 0, 0x14000
	ds_read_b128 v[140:143], v148
	ds_read_b128 v[144:147], v148 offset:1024
	ds_read_b128 v[154:157], v148 offset:2048
	ds_read_b128 v[158:161], v148 offset:3072
	v_add_u32_e32 v148, vcc_lo, v151
	ds_read_b128 v[162:165], v148
	ds_read_b128 v[166:169], v148 offset:1024
	ds_read_b128 v[170:173], v148 offset:2048
	ds_read_b128 v[174:177], v148 offset:3072
	v_lshl_add_u64 v[148:149], s[30:31], 0, v[136:137]
	s_add_i32 m0, s72, 0xc000
	ds_read_b128 v[178:181], v153
	ds_read_b128 v[182:185], v153 offset:1024
	ds_read_b128 v[186:189], v153 offset:2048
	ds_read_b128 v[190:193], v153 offset:3072
	ds_read_b128 v[194:197], v153 offset:4096
	ds_read_b128 v[208:211], v153 offset:5120
	ds_read_b128 v[212:215], v153 offset:6144
	ds_read_b128 v[226:229], v153 offset:7168
	global_load_lds_dwordx4 v[148:149], off
	v_lshl_add_u64 v[148:149], s[30:31], 0, v[138:139]
	s_add_i32 m0, s72, 0xe000
	s_nop 0
	global_load_lds_dwordx4 v[148:149], off
	s_waitcnt vmcnt(8)
	s_waitcnt lgkmcnt(0)
	s_barrier
	s_setprio 1
	s_waitcnt lgkmcnt(0)
	v_mfma_f32_16x16x32_bf16 v[126:129], v[140:143], v[178:181], v[126:129]
	v_mfma_f32_16x16x32_bf16 v[122:125], v[154:157], v[178:181], v[122:125]
	v_mfma_f32_16x16x32_bf16 v[110:113], v[140:143], v[186:189], v[110:113]
	v_mfma_f32_16x16x32_bf16 v[106:109], v[154:157], v[186:189], v[106:109]
	v_mfma_f32_16x16x32_bf16 v[94:97], v[140:143], v[194:197], v[94:97]
	v_mfma_f32_16x16x32_bf16 v[90:93], v[154:157], v[194:197], v[90:93]
	v_mfma_f32_16x16x32_bf16 v[78:81], v[140:143], v[212:215], v[78:81]
	v_mfma_f32_16x16x32_bf16 v[74:77], v[154:157], v[212:215], v[74:77]
	v_mfma_f32_16x16x32_bf16 v[126:129], v[144:147], v[182:185], v[126:129]
	v_mfma_f32_16x16x32_bf16 v[122:125], v[158:161], v[182:185], v[122:125]
	v_mfma_f32_16x16x32_bf16 v[110:113], v[144:147], v[190:193], v[110:113]
	v_mfma_f32_16x16x32_bf16 v[106:109], v[158:161], v[190:193], v[106:109]
	v_mfma_f32_16x16x32_bf16 v[94:97], v[144:147], v[208:211], v[94:97]
	v_mfma_f32_16x16x32_bf16 v[90:93], v[158:161], v[208:211], v[90:93]
	v_mfma_f32_16x16x32_bf16 v[78:81], v[144:147], v[226:229], v[78:81]
	v_mfma_f32_16x16x32_bf16 v[74:77], v[158:161], v[226:229], v[74:77]
	s_setprio 0
	s_setprio 1
	v_mfma_f32_16x16x32_bf16 v[118:121], v[162:165], v[178:181], v[118:121]
	v_mfma_f32_16x16x32_bf16 v[114:117], v[170:173], v[178:181], v[114:117]
	v_mfma_f32_16x16x32_bf16 v[102:105], v[162:165], v[186:189], v[102:105]
	v_mfma_f32_16x16x32_bf16 v[98:101], v[170:173], v[186:189], v[98:101]
	v_mfma_f32_16x16x32_bf16 v[86:89], v[162:165], v[194:197], v[86:89]
	v_mfma_f32_16x16x32_bf16 v[82:85], v[170:173], v[194:197], v[82:85]
	v_mfma_f32_16x16x32_bf16 v[70:73], v[162:165], v[212:215], v[70:73]
	v_mfma_f32_16x16x32_bf16 v[66:69], v[170:173], v[212:215], v[66:69]
	v_mfma_f32_16x16x32_bf16 v[118:121], v[166:169], v[182:185], v[118:121]
	v_mfma_f32_16x16x32_bf16 v[114:117], v[174:177], v[182:185], v[114:117]
	v_mfma_f32_16x16x32_bf16 v[102:105], v[166:169], v[190:193], v[102:105]
	v_mfma_f32_16x16x32_bf16 v[98:101], v[174:177], v[190:193], v[98:101]
	v_mfma_f32_16x16x32_bf16 v[86:89], v[166:169], v[208:211], v[86:89]
	v_mfma_f32_16x16x32_bf16 v[82:85], v[174:177], v[208:211], v[82:85]
	v_mfma_f32_16x16x32_bf16 v[70:73], v[166:169], v[226:229], v[70:73]
	v_mfma_f32_16x16x32_bf16 v[66:69], v[174:177], v[226:229], v[66:69]
	s_setprio 0
	s_barrier
	s_add_i32 s86, s86, s71
	v_lshl_add_u64 v[148:149], s[58:59], 0, v[24:25]
	s_mov_b32 m0, s86
	ds_read_b128 v[178:181], v153 offset:16384
	ds_read_b128 v[182:185], v153 offset:17408
	ds_read_b128 v[186:189], v153 offset:18432
	ds_read_b128 v[190:193], v153 offset:19456
	ds_read_b128 v[194:197], v153 offset:20480
	ds_read_b128 v[208:211], v153 offset:21504
	ds_read_b128 v[212:215], v153 offset:22528
	ds_read_b128 v[226:229], v153 offset:23552
	global_load_lds_dwordx4 v[148:149], off
	s_add_i32 m0, s86, 0x2000
	s_add_u32 s86, s58, 0x200000
	v_lshl_add_u64 v[206:207], s[58:59], 0, v[134:135]
	s_addc_u32 s87, s59, 0
	s_add_i32 vcc_lo, vcc_lo, s71
	global_load_lds_dwordx4 v[206:207], off
	v_lshl_add_u64 v[216:217], s[86:87], 0, v[24:25]
	s_mov_b32 m0, vcc_lo
	v_lshl_add_u64 v[230:231], s[60:61], 0, v[132:133]
	global_load_lds_dwordx4 v[216:217], off
	v_lshl_add_u64 v[216:217], s[86:87], 0, v[134:135]
	s_add_i32 m0, vcc_lo, 0x2000
	s_nop 0
	global_load_lds_dwordx4 v[216:217], off
	v_lshl_add_u64 v[216:217], s[60:61], 0, v[130:131]
	s_mov_b32 m0, s72
	s_nop 0
	global_load_lds_dwordx4 v[216:217], off
	s_mov_b32 m0, s73
	s_nop 0
	global_load_lds_dwordx4 v[230:231], off
	s_waitcnt vmcnt(8)
	s_waitcnt lgkmcnt(0)
	s_barrier
; #define PG8_STAGE(bufoff, gbase, voff) do { _Pragma("unroll") for (int _i = 0; _i < 2; ++_i) \
;         __builtin_amdgcn_global_load_lds((const unsigned*)((const char*)(gbase) + (voff)[_i]), (LAS unsigned*)(lds + (bufoff) + ldsw + _i * 8192), 16, 0, 0); } while (0)
; #define PG8_LDA(dst, b, h) do { _Pragma("unroll") for (int m = 0; m < 4; ++m) _Pragma("unroll") for (int k = 0; k < 2; ++k) dst[m][k] = *(const LAS bf16x8*)(lds + PG8_SA(b, h) + aoff + m * 2048 + k * 1024); } while (0)
; #define PG8_LDB(dst, b, h) do { _Pragma("unroll") for (int n = 0; n < 2; ++n) _Pragma("unroll") for (int k = 0; k < 2; ++k) dst[n][k] = *(const LAS bf16x8*)(lds + PG8_SB(b, h) + boff + n * 2048 + k * 1024); } while (0)
; #define PG8_MMA(ai, bj, At, Bt) do { __builtin_amdgcn_s_setprio(1); _Pragma("unroll") for (int m = 0; m < 4; ++m) _Pragma("unroll") for (int n = 0; n < 2; ++n) _Pragma("unroll") for (int k = 0; k < 2; ++k) \
;         acc[ai][bj][m][n] = __builtin_amdgcn_mfma_f32_16x16x32_bf16(Bt[n][k], At[m][k], acc[ai][bj][m][n], 0, 0, 0); __builtin_amdgcn_s_setprio(0); } while (0)
; #define PG8_WAIT_V(n) asm volatile("s_waitcnt vmcnt(" #n ")" ::: "memory")
; #define PG8_WAIT_L(n) asm volatile("s_waitcnt lgkmcnt(" #n ")" ::: "memory")
; #define PG8_BAR __builtin_amdgcn_s_barrier()
; #define PG8_SCHED __builtin_amdgcn_sched_barrier(0)
; template <class Epi, class Sched, bool HN = false>
; __device__ __forceinline__ void gemm_phase(LAS unsigned char* lds, const Gemm g, const Sched& S, const Epi& E) {
;     ...
;             PG8_WAIT_V(8); PG8_WAIT_L(0); PG8_BAR; PG8_MMA(1, 0, At, B0); PG8_MMA(1, 1, At, B1); PG8_BAR; PG8_SCHED;
;             PG8_LDB(B0, 1, 0); PG8_LDB(B1, 1, 1); PG8_SCHED; PG8_LDA(At, 1, 0); PG8_STAGE(PG8_SA(0, 1), a2 + hstep, voffA);
;             PG8_WAIT_V(8); PG8_WAIT_L(0); PG8_BAR; PG8_MMA(0, 0, At, B0); PG8_MMA(0, 1, At, B1); PG8_BAR; PG8_SCHED;
	s_setprio 1
	s_waitcnt lgkmcnt(0)
	v_mfma_f32_16x16x32_bf16 v[62:65], v[140:143], v[178:181], v[62:65]
	v_mfma_f32_16x16x32_bf16 v[58:61], v[154:157], v[178:181], v[58:61]
	v_mfma_f32_16x16x32_bf16 v[46:49], v[140:143], v[186:189], v[46:49]
	v_mfma_f32_16x16x32_bf16 v[42:45], v[154:157], v[186:189], v[42:45]
	v_mfma_f32_16x16x32_bf16 v[30:33], v[140:143], v[194:197], v[30:33]
	v_mfma_f32_16x16x32_bf16 v[26:29], v[154:157], v[194:197], v[26:29]
	v_mfma_f32_16x16x32_bf16 v[12:15], v[140:143], v[212:215], v[12:15]
	v_mfma_f32_16x16x32_bf16 v[8:11], v[154:157], v[212:215], v[8:11]
	v_mfma_f32_16x16x32_bf16 v[62:65], v[144:147], v[182:185], v[62:65]
	v_mfma_f32_16x16x32_bf16 v[58:61], v[158:161], v[182:185], v[58:61]
	v_mfma_f32_16x16x32_bf16 v[46:49], v[144:147], v[190:193], v[46:49]
	v_mfma_f32_16x16x32_bf16 v[42:45], v[158:161], v[190:193], v[42:45]
	v_mfma_f32_16x16x32_bf16 v[30:33], v[144:147], v[208:211], v[30:33]
	v_mfma_f32_16x16x32_bf16 v[26:29], v[158:161], v[208:211], v[26:29]
	v_mfma_f32_16x16x32_bf16 v[12:15], v[144:147], v[226:229], v[12:15]
	v_mfma_f32_16x16x32_bf16 v[8:11], v[158:161], v[226:229], v[8:11]
	s_setprio 0
	s_setprio 1
	v_mfma_f32_16x16x32_bf16 v[54:57], v[162:165], v[178:181], v[54:57]
	v_mfma_f32_16x16x32_bf16 v[50:53], v[170:173], v[178:181], v[50:53]
	v_mfma_f32_16x16x32_bf16 v[38:41], v[162:165], v[186:189], v[38:41]
	v_mfma_f32_16x16x32_bf16 v[34:37], v[170:173], v[186:189], v[34:37]
	v_mfma_f32_16x16x32_bf16 v[20:23], v[162:165], v[194:197], v[20:23]
	v_mfma_f32_16x16x32_bf16 v[16:19], v[170:173], v[194:197], v[16:19]
	v_mfma_f32_16x16x32_bf16 v[4:7], v[162:165], v[212:215], v[4:7]
	v_mfma_f32_16x16x32_bf16 v[0:3], v[170:173], v[212:215], v[0:3]
	v_mfma_f32_16x16x32_bf16 v[54:57], v[166:169], v[182:185], v[54:57]
	v_mfma_f32_16x16x32_bf16 v[50:53], v[174:177], v[182:185], v[50:53]
	v_mfma_f32_16x16x32_bf16 v[38:41], v[166:169], v[190:193], v[38:41]
	v_mfma_f32_16x16x32_bf16 v[34:37], v[174:177], v[190:193], v[34:37]
	v_mfma_f32_16x16x32_bf16 v[20:23], v[166:169], v[208:211], v[20:23]
	v_mfma_f32_16x16x32_bf16 v[16:19], v[174:177], v[208:211], v[16:19]
	v_mfma_f32_16x16x32_bf16 v[4:7], v[166:169], v[226:229], v[4:7]
	v_mfma_f32_16x16x32_bf16 v[0:3], v[174:177], v[226:229], v[0:3]
	s_setprio 0
	s_barrier
	s_add_i32 s86, 0, 0x18000
	s_add_i32 s87, 0, 0x1c000
	v_add_u32_e32 v158, s86, v151
	v_add_u32_e32 v174, s87, v151
	ds_read_b128 v[140:143], v158
	ds_read_b128 v[144:147], v158 offset:1024
	ds_read_b128 v[154:157], v158 offset:2048
	ds_read_b128 v[158:161], v158 offset:3072
	ds_read_b128 v[162:165], v174
	ds_read_b128 v[166:169], v174 offset:1024
	ds_read_b128 v[170:173], v174 offset:2048
	ds_read_b128 v[174:177], v174 offset:3072
	s_add_u32 s60, s60, 0x200000
	s_addc_u32 s61, s61, 0
	s_mov_b32 m0, s76
	v_lshl_add_u64 v[232:233], s[60:61], 0, v[130:131]
	ds_read_b128 v[178:181], v153 offset:32768
	ds_read_b128 v[182:185], v153 offset:33792
	ds_read_b128 v[186:189], v153 offset:34816
	ds_read_b128 v[190:193], v153 offset:35840
	ds_read_b128 v[194:197], v153 offset:36864
	ds_read_b128 v[208:211], v153 offset:37888
	ds_read_b128 v[212:215], v153 offset:38912
	ds_read_b128 v[226:229], v153 offset:39936
	global_load_lds_dwordx4 v[232:233], off
	v_lshl_add_u64 v[232:233], s[60:61], 0, v[132:133]
	s_mov_b32 m0, s77
	s_nop 0
	global_load_lds_dwordx4 v[232:233], off
	s_waitcnt vmcnt(8)
	s_waitcnt lgkmcnt(0)
	s_barrier
	s_setprio 1
	s_waitcnt lgkmcnt(0)
	v_mfma_f32_16x16x32_bf16 v[126:129], v[140:143], v[178:181], v[126:129]
	v_mfma_f32_16x16x32_bf16 v[122:125], v[154:157], v[178:181], v[122:125]
	v_mfma_f32_16x16x32_bf16 v[110:113], v[140:143], v[186:189], v[110:113]
	v_mfma_f32_16x16x32_bf16 v[106:109], v[154:157], v[186:189], v[106:109]
	v_mfma_f32_16x16x32_bf16 v[94:97], v[140:143], v[194:197], v[94:97]
	v_mfma_f32_16x16x32_bf16 v[90:93], v[154:157], v[194:197], v[90:93]
	v_mfma_f32_16x16x32_bf16 v[78:81], v[140:143], v[212:215], v[78:81]
	v_mfma_f32_16x16x32_bf16 v[74:77], v[154:157], v[212:215], v[74:77]
	v_mfma_f32_16x16x32_bf16 v[126:129], v[144:147], v[182:185], v[126:129]
	v_mfma_f32_16x16x32_bf16 v[122:125], v[158:161], v[182:185], v[122:125]
	v_mfma_f32_16x16x32_bf16 v[110:113], v[144:147], v[190:193], v[110:113]
	v_mfma_f32_16x16x32_bf16 v[106:109], v[158:161], v[190:193], v[106:109]
	v_mfma_f32_16x16x32_bf16 v[94:97], v[144:147], v[208:211], v[94:97]
	v_mfma_f32_16x16x32_bf16 v[90:93], v[158:161], v[208:211], v[90:93]
	v_mfma_f32_16x16x32_bf16 v[78:81], v[144:147], v[226:229], v[78:81]
	v_mfma_f32_16x16x32_bf16 v[74:77], v[158:161], v[226:229], v[74:77]
	s_setprio 0
	s_setprio 1
	v_mfma_f32_16x16x32_bf16 v[118:121], v[162:165], v[178:181], v[118:121]
	v_mfma_f32_16x16x32_bf16 v[114:117], v[170:173], v[178:181], v[114:117]
	v_mfma_f32_16x16x32_bf16 v[102:105], v[162:165], v[186:189], v[102:105]
	v_mfma_f32_16x16x32_bf16 v[98:101], v[170:173], v[186:189], v[98:101]
	v_mfma_f32_16x16x32_bf16 v[86:89], v[162:165], v[194:197], v[86:89]
	v_mfma_f32_16x16x32_bf16 v[82:85], v[170:173], v[194:197], v[82:85]
	v_mfma_f32_16x16x32_bf16 v[70:73], v[162:165], v[212:215], v[70:73]
	v_mfma_f32_16x16x32_bf16 v[66:69], v[170:173], v[212:215], v[66:69]
	v_mfma_f32_16x16x32_bf16 v[118:121], v[166:169], v[182:185], v[118:121]
	v_mfma_f32_16x16x32_bf16 v[114:117], v[174:177], v[182:185], v[114:117]
	v_mfma_f32_16x16x32_bf16 v[102:105], v[166:169], v[190:193], v[102:105]
	v_mfma_f32_16x16x32_bf16 v[98:101], v[174:177], v[190:193], v[98:101]
	v_mfma_f32_16x16x32_bf16 v[86:89], v[166:169], v[208:211], v[86:89]
	v_mfma_f32_16x16x32_bf16 v[82:85], v[174:177], v[208:211], v[82:85]
	v_mfma_f32_16x16x32_bf16 v[70:73], v[166:169], v[226:229], v[70:73]
	v_mfma_f32_16x16x32_bf16 v[66:69], v[174:177], v[226:229], v[66:69]
	s_setprio 0
	s_barrier
; #define PG8_STAGE(bufoff, gbase, voff) do { _Pragma("unroll") for (int _i = 0; _i < 2; ++_i) \
;         __builtin_amdgcn_global_load_lds((const unsigned*)((const char*)(gbase) + (voff)[_i]), (LAS unsigned*)(lds + (bufoff) + ldsw + _i * 8192), 16, 0, 0); } while (0)
; #define PG8_LDA(dst, b, h) do { _Pragma("unroll") for (int m = 0; m < 4; ++m) _Pragma("unroll") for (int k = 0; k < 2; ++k) dst[m][k] = *(const LAS bf16x8*)(lds + PG8_SA(b, h) + aoff + m * 2048 + k * 1024); } while (0)
; #define PG8_MMA(ai, bj, At, Bt) do { __builtin_amdgcn_s_setprio(1); _Pragma("unroll") for (int m = 0; m < 4; ++m) _Pragma("unroll") for (int n = 0; n < 2; ++n) _Pragma("unroll") for (int k = 0; k < 2; ++k) \
;         acc[ai][bj][m][n] = __builtin_amdgcn_mfma_f32_16x16x32_bf16(Bt[n][k], At[m][k], acc[ai][bj][m][n], 0, 0, 0); __builtin_amdgcn_s_setprio(0); } while (0)
; #define PG8_WAIT_V(n) asm volatile("s_waitcnt vmcnt(" #n ")" ::: "memory")
; #define PG8_WAIT_L(n) asm volatile("s_waitcnt lgkmcnt(" #n ")" ::: "memory")
; #define PG8_BAR __builtin_amdgcn_s_barrier()
; #define PG8_SCHED __builtin_amdgcn_sched_barrier(0)
; template <class Epi, class Sched, bool HN = false>
; __device__ __forceinline__ void gemm_phase(LAS unsigned char* lds, const Gemm g, const Sched& S, const Epi& E) {
;     ...
;         for (int t = 0; t < nt; t += 2) {
;             const bool last = (t == nt - 2);
;             const char* a1 = cA + (size_t)(t + 1) * kstep;
;             const char* a2 = last ? nA : cA + (size_t)(t + 2) * kstep; const char* b2 = last ? nB : cB + (size_t)(t + 2) * kstep;
;     ...
;             PG8_LDA(At, 1, 1); PG8_STAGE(PG8_SB(1, 0), b3, voffB); PG8_STAGE(PG8_SB(1, 1), b3 + hstep, voffB); PG8_STAGE(PG8_SA(1, 0), a3, voffA);
;             PG8_WAIT_V(8); PG8_WAIT_L(0); PG8_BAR; PG8_MMA(1, 0, At, B0); PG8_MMA(1, 1, At, B1); PG8_BAR; PG8_SCHED;
	s_add_i32 s60, s86, s71
	v_lshl_add_u64 v[148:149], v[148:149], 0, s[28:29]
	s_mov_b32 m0, s60
	ds_read_b128 v[178:181], v153 offset:49152
	ds_read_b128 v[182:185], v153 offset:50176
	ds_read_b128 v[186:189], v153 offset:51200
	ds_read_b128 v[190:193], v153 offset:52224
	ds_read_b128 v[194:197], v153 offset:53248
	ds_read_b128 v[208:211], v153 offset:54272
	ds_read_b128 v[212:215], v153 offset:55296
	ds_read_b128 v[226:229], v153 offset:56320
	global_load_lds_dwordx4 v[148:149], off
	s_add_i32 m0, s60, 0x2000
	s_add_u32 s58, s58, 0x200080
	v_lshl_add_u64 v[148:149], v[206:207], 0, s[28:29]
	s_addc_u32 s59, s59, 0
	s_add_i32 s60, s87, s71
	global_load_lds_dwordx4 v[148:149], off
	v_lshl_add_u64 v[148:149], s[58:59], 0, v[24:25]
	s_mov_b32 m0, s60
	s_nop 0
	global_load_lds_dwordx4 v[148:149], off
	v_lshl_add_u64 v[148:149], s[58:59], 0, v[134:135]
	s_add_i32 m0, s60, 0x2000
	s_nop 0
	global_load_lds_dwordx4 v[148:149], off
	v_lshl_add_u64 v[148:149], v[216:217], 0, s[28:29]
	s_mov_b32 m0, s83
	s_nop 0
	global_load_lds_dwordx4 v[148:149], off
	v_lshl_add_u64 v[148:149], v[230:231], 0, s[28:29]
	s_mov_b32 m0, s36
	s_nop 0
	global_load_lds_dwordx4 v[148:149], off
	s_waitcnt vmcnt(8)
	s_waitcnt lgkmcnt(0)
	s_barrier
	s_setprio 1
	s_waitcnt lgkmcnt(0)
	v_mfma_f32_16x16x32_bf16 v[62:65], v[140:143], v[178:181], v[62:65]
	v_mfma_f32_16x16x32_bf16 v[58:61], v[154:157], v[178:181], v[58:61]
	v_mfma_f32_16x16x32_bf16 v[46:49], v[140:143], v[186:189], v[46:49]
	v_mfma_f32_16x16x32_bf16 v[42:45], v[154:157], v[186:189], v[42:45]
	v_mfma_f32_16x16x32_bf16 v[30:33], v[140:143], v[194:197], v[30:33]
	v_mfma_f32_16x16x32_bf16 v[26:29], v[154:157], v[194:197], v[26:29]
	v_mfma_f32_16x16x32_bf16 v[12:15], v[140:143], v[212:215], v[12:15]
	v_mfma_f32_16x16x32_bf16 v[8:11], v[154:157], v[212:215], v[8:11]
	v_mfma_f32_16x16x32_bf16 v[62:65], v[144:147], v[182:185], v[62:65]
	v_mfma_f32_16x16x32_bf16 v[58:61], v[158:161], v[182:185], v[58:61]
	v_mfma_f32_16x16x32_bf16 v[46:49], v[144:147], v[190:193], v[46:49]
	v_mfma_f32_16x16x32_bf16 v[42:45], v[158:161], v[190:193], v[42:45]
	v_mfma_f32_16x16x32_bf16 v[30:33], v[144:147], v[208:211], v[30:33]
	v_mfma_f32_16x16x32_bf16 v[26:29], v[158:161], v[208:211], v[26:29]
	v_mfma_f32_16x16x32_bf16 v[12:15], v[144:147], v[226:229], v[12:15]
	v_mfma_f32_16x16x32_bf16 v[8:11], v[158:161], v[226:229], v[8:11]
	s_setprio 0
	s_setprio 1
	v_mfma_f32_16x16x32_bf16 v[54:57], v[162:165], v[178:181], v[54:57]
	v_mfma_f32_16x16x32_bf16 v[50:53], v[170:173], v[178:181], v[50:53]
	v_mfma_f32_16x16x32_bf16 v[38:41], v[162:165], v[186:189], v[38:41]
	v_mfma_f32_16x16x32_bf16 v[34:37], v[170:173], v[186:189], v[34:37]
	v_mfma_f32_16x16x32_bf16 v[20:23], v[162:165], v[194:197], v[20:23]
	v_mfma_f32_16x16x32_bf16 v[16:19], v[170:173], v[194:197], v[16:19]
	v_mfma_f32_16x16x32_bf16 v[4:7], v[162:165], v[212:215], v[4:7]
	v_mfma_f32_16x16x32_bf16 v[0:3], v[170:173], v[212:215], v[0:3]
	v_mfma_f32_16x16x32_bf16 v[54:57], v[166:169], v[182:185], v[54:57]
	v_mfma_f32_16x16x32_bf16 v[50:53], v[174:177], v[182:185], v[50:53]
	v_mfma_f32_16x16x32_bf16 v[38:41], v[166:169], v[190:193], v[38:41]
	v_mfma_f32_16x16x32_bf16 v[34:37], v[174:177], v[190:193], v[34:37]
	v_mfma_f32_16x16x32_bf16 v[20:23], v[166:169], v[208:211], v[20:23]
	v_mfma_f32_16x16x32_bf16 v[16:19], v[174:177], v[208:211], v[16:19]
	v_mfma_f32_16x16x32_bf16 v[4:7], v[166:169], v[226:229], v[4:7]
	v_mfma_f32_16x16x32_bf16 v[0:3], v[174:177], v[226:229], v[0:3]
	s_setprio 0
	s_add_i32 s85, s85, 2
	s_add_u32 s30, s30, 0x100
	s_addc_u32 s31, s31, 0
	s_add_u32 s74, s74, 0x100
	s_addc_u32 s84, s84, 0
	s_cmpk_gt_u32 s85, 0x7d
	s_barrier
	s_cbranch_scc0 .LBB0_1357
	s_and_b64 vcc, exec, s[34:35]
	s_cbranch_vccz .LBB0_1360
	s_barrier
